# P2/P5/P7 K-loops: v_mfma_f32_16x16x32_bf16 instead of 32x32x16 (same bf16 operands, f32 accumulate, same tile), conflict-free swizzled 16-row fragment reads, permlane fixup restores the 32x32 accumula
# speedup vs baseline: 1.0078x; 1.0078x over previous
; template <bool SWAP, class Epi>
; DI void gemm_tile(const u16* __restrict__ A, int lda, const u16* __restrict__ Bt, int ldb, int K, int m0, int n0, char* smem, Epi&& epi) {
;     ...
;   const int tid = threadIdx.x, lane = tid & 63, w = tid >> 6, wm = w >> 1, wn = w & 1;
;   const int r = lane & 31, hi = lane >> 5;
;   f32x16 acc[2][2];
; #pragma unroll
;   for (int a = 0; a < 2; ++a)
; #pragma unroll
;     for (int b = 0; b < 2; ++b)
; #pragma unroll
;       for (int i = 0; i < 16; ++i) acc[a][b][i] = 0.f;
;   const int srow = tid >> 3, skc = tid & 7;
;   const u16* ag = A + (size_t)(m0 + srow) * lda + skc * 8;
;   const u16* bg = Bt + (size_t)(n0 + srow) * ldb + skc * 8;
;   u16* asw = As + srow * 72 + skc * 8;
;   u16* bsw = Bs + srow * 72 + skc * 8;
;   u32x4 ra0[4], rb0[4], ra1[4], rb1[4];
; #pragma unroll
;   for (int i = 0; i < 4; ++i) { ra0[i] = *(const u32x4*)(ag + (size_t)i * 32 * lda); rb0[i] = *(const u32x4*)(bg + (size_t)i * 32 * ldb); }
; #pragma unroll
;   for (int i = 0; i < 4; ++i) { ra1[i] = *(const u32x4*)(ag + (size_t)i * 32 * lda + 64); rb1[i] = *(const u32x4*)(bg + (size_t)i * 32 * ldb + 64); }
;   __syncthreads();
; #pragma unroll
;   for (int i = 0; i < 4; ++i) { *(u32x4*)(asw + 32 * i * 72) = ra0[i]; *(u32x4*)(bsw + 32 * i * 72) = rb0[i]; }
;   __syncthreads();
;   const int KT = K >> 6;
;   const u16* Asb = As + (wm * 64 + r) * 72 + hi * 8;
;   const u16* Bsb = Bs + (wn * 64 + r) * 72 + hi * 8;
; DI void phase2(const Params& p, char* smem, int rep) {
;     ...
;   for (int it = blockIdx.x; it < 64 * 32; it += gridDim.x) {
;     const int tn = it / 64, tm = it % 64;
;     gemm_tile<true>(H, D_, W, D_, D_, tm * 128, tn * 128, smem, [&](f32x16 (&acc)[2][2], int mb, int nb, int r, int hi) __attribute__((always_inline)) {
.Lprio_p2:
	s_cmpk_gt_i32 s12, 0x7ff
	s_cbranch_scc1 .LBB0_398
	v_lshlrev_b32_e32 v2, 4, v0
	v_and_b32_e32 v130, 0x70, v2
	v_mov_b32_e32 v131, 0
	v_lshl_add_u64 v[2:3], s[82:83], 0, v[130:131]
	s_mov_b64 s[2:3], 0x6538000
	v_lshrrev_b32_e32 v1, 3, v0
	v_lshl_add_u64 v[132:133], v[2:3], 0, s[2:3]
	s_mov_b64 s[2:3], 0xb8000
	v_lshl_add_u64 v[134:135], v[2:3], 0, s[2:3]
	v_mul_u32_u24_e32 v2, 0x48, v1
	v_and_b32_e32 v4, 31, v0
	v_lshlrev_b32_e32 v2, 1, v2
	v_lshrrev_b32_e32 v3, 1, v0
	v_add3_u32 v146, 0, v2, v130
	v_bfe_u32 v2, v0, 5, 1
	v_and_or_b32 v148, v3, 64, v4
	s_load_dword s13, s[0:1], 0xc0
	s_add_u32 s4, s82, 0x8538000
	v_mul_u32_u24_e32 v3, 0x90, v148
	v_lshlrev_b32_e32 v4, 4, v2
	s_addc_u32 s5, s83, 0
	v_add3_u32 v149, 0, v3, v4
	v_and_b32_e32 v3, 0x5f, v0
	v_lshlrev_b32_e32 v152, 2, v2
	v_cmp_eq_u32_e64 s[2:3], 0, v2
	v_and_b32_e32 v2, 7, v0
	s_add_u32 s6, s82, 0x18320000
	v_mul_u32_u24_e32 v3, 0x90, v3
	v_lshlrev_b32_e32 v136, 4, v2
	v_mbcnt_lo_u32_b32 v2, -1, 0
	s_addc_u32 s7, s83, 0
	v_add_u32_e32 v147, 0x9010, v146
	v_add3_u32 v150, 0, v3, v4
	v_and_b32_e32 v151, 64, v0
	v_mov_b32_e32 v137, v131
	s_mov_b32 s16, 0x20000
	s_mov_b32 s17, 0x40000
	s_mov_b32 s18, 0x60000
	s_mov_b64 s[8:9], 0x100
	s_movk_i32 s19, 0x2080
	s_movk_i32 s20, 0xbff
	v_mbcnt_hi_u32_b32 v153, -1, v2
	s_mov_b32 s21, s12
	v_lshrrev_b32_e32 v198, 3, v0
	v_lshrrev_b32_e32 v199, 2, v198
	v_lshrrev_b32_e32 v200, 3, v198
	v_xor_b32_e32 v199, v199, v200
	v_and_b32_e32 v199, 1, v199
	v_and_b32_e32 v200, 1, v0
	v_lshlrev_b32_e32 v200, 5, v200
	v_sub_u32_e32 v200, 16, v200
	v_mul_lo_u32 v199, v199, v200
	v_add_u32_e32 v146, v146, v199
	v_add_u32_e32 v147, v147, v199
	v_and_b32_e32 v198, 15, v0
	v_bfe_u32 v199, v0, 4, 2
	v_lshrrev_b32_e32 v200, 2, v198
	v_lshrrev_b32_e32 v201, 3, v198
	v_xor_b32_e32 v200, v200, v201
	v_and_b32_e32 v200, 1, v200
	v_xor_b32_e32 v199, v199, v200
	v_lshlrev_b32_e32 v199, 4, v199
	v_bfe_u32 v200, v0, 7, 1
	v_lshl_or_b32 v200, v200, 6, v198
	v_mul_u32_u24_e32 v200, 0x90, v200
	v_add_u32_e32 v149, v200, v199
	v_bfe_u32 v200, v0, 6, 1
	v_lshl_or_b32 v200, v200, 6, v198
	v_mul_u32_u24_e32 v200, 0x90, v200
	v_add_u32_e32 v150, v200, v199
	s_branch .LBB0_385

; #define MFMA(a, b, c) __builtin_amdgcn_mfma_f32_32x32x16_bf16((a), (b), (c), 0, 0, 0)
; template <bool SWAP, class Epi>
; DI void gemm_tile(const u16* __restrict__ A, int lda, const u16* __restrict__ Bt, int ldb, int K, int m0, int n0, char* smem, Epi&& epi) {
;     ...
;   auto compute = [&](int buf) __attribute__((always_inline)) {
;     bf16x8 af[2][2], bfr[2][2];
;     af[0][0] = *(const bf16x8*)(Asb + buf * 128 * 72);
;     af[0][1] = *(const bf16x8*)(Asb + buf * 128 * 72 + 32 * 72);
;     bfr[0][0] = *(const bf16x8*)(Bsb + buf * 128 * 72);
;     bfr[0][1] = *(const bf16x8*)(Bsb + buf * 128 * 72 + 32 * 72);
; #pragma unroll
;     for (int ks = 0; ks < 4; ++ks) {
;       const int c = ks & 1, n = c ^ 1;
;       if (ks < 3) {
;         af[n][0] = *(const bf16x8*)(Asb + buf * 128 * 72 + (ks + 1) * 16);
;         af[n][1] = *(const bf16x8*)(Asb + buf * 128 * 72 + 32 * 72 + (ks + 1) * 16);
;         bfr[n][0] = *(const bf16x8*)(Bsb + buf * 128 * 72 + (ks + 1) * 16);
;         bfr[n][1] = *(const bf16x8*)(Bsb + buf * 128 * 72 + 32 * 72 + (ks + 1) * 16);
;       }
;       __builtin_amdgcn_sched_barrier(0);
; #pragma unroll
;       for (int mi = 0; mi < 2; ++mi)
; #pragma unroll
;         for (int ni = 0; ni < 2; ++ni) {
;           if (SWAP) acc[mi][ni] = MFMA(bfr[c][ni], af[c][mi], acc[mi][ni]);
;           else acc[mi][ni] = MFMA(af[c][mi], bfr[c][ni], acc[mi][ni]);
;         }
;       __builtin_amdgcn_sched_barrier(0);
;     }
;   };
;   for (int kt = 0; kt < KT; kt += 2) {
;     if (kt + 2 < KT) {
;       const int k0 = (kt + 2) << 6;
; #pragma unroll
;       for (int i = 0; i < 4; ++i) { ra0[i] = *(const u32x4*)(ag + (size_t)i * 32 * lda + k0); rb0[i] = *(const u32x4*)(bg + (size_t)i * 32 * ldb + k0); }
;     }
;     compute(0);
; #pragma unroll
;     for (int i = 0; i < 4; ++i) { *(u32x4*)(asw + 128 * 72 + 32 * i * 72) = ra1[i]; *(u32x4*)(bsw + 128 * 72 + 32 * i * 72) = rb1[i]; }
;     __syncthreads();
;     if (kt + 3 < KT) {
;       const int k0 = (kt + 3) << 6;
; #pragma unroll
;       for (int i = 0; i < 4; ++i) { ra1[i] = *(const u32x4*)(ag + (size_t)i * 32 * lda + k0); rb1[i] = *(const u32x4*)(bg + (size_t)i * 32 * ldb + k0); }
;     }
;     compute(1);
;     if (kt + 2 < KT) {
; #pragma unroll
;       for (int i = 0; i < 4; ++i) { *(u32x4*)(asw + 32 * i * 72) = ra0[i]; *(u32x4*)(bsw + 32 * i * 72) = rb0[i]; }
;     }
;     __syncthreads();
;   }
.LBB0_387:
	global_load_dwordx4 v[66:69], v194, s[100:101] offset:256
	global_load_dwordx4 v[70:73], v190, s[98:99] offset:256
	global_load_dwordx4 v[74:77], v195, s[100:101] offset:256
	global_load_dwordx4 v[78:81], v191, s[98:99] offset:256
	global_load_dwordx4 v[82:85], v196, s[100:101] offset:256
	global_load_dwordx4 v[86:89], v192, s[98:99] offset:256
	global_load_dwordx4 v[90:93], v197, s[100:101] offset:256
	global_load_dwordx4 v[94:97], v193, s[98:99] offset:256
	ds_read_b128 v[170:173], v150 offset:36880
	ds_read_b128 v[154:157], v149 offset:16
	ds_read_b128 v[158:161], v149 offset:2320
	ds_read_b128 v[174:177], v150 offset:39184
	ds_read_b128 v[162:165], v149 offset:4624
	ds_read_b128 v[166:169], v149 offset:6928
	ds_read_b128 v[178:181], v150 offset:41488
	ds_read_b128 v[182:185], v150 offset:43792
	s_waitcnt lgkmcnt(6)
	v_mfma_f32_16x16x32_bf16 v[50:53], v[170:173], v[154:157], v[50:53]
	s_waitcnt lgkmcnt(5)
	v_mfma_f32_16x16x32_bf16 v[54:57], v[170:173], v[158:161], v[54:57]
	s_waitcnt lgkmcnt(4)
	v_mfma_f32_16x16x32_bf16 v[58:61], v[174:177], v[154:157], v[58:61]
	v_mfma_f32_16x16x32_bf16 v[62:65], v[174:177], v[158:161], v[62:65]
	ds_read_b128 v[214:217], v150 offset:36944
	ds_read_b128 v[198:201], v149 offset:80
	ds_read_b128 v[202:205], v149 offset:2384
	ds_read_b128 v[218:221], v150 offset:39248
	s_waitcnt lgkmcnt(7)
	v_mfma_f32_16x16x32_bf16 v[18:21], v[170:173], v[162:165], v[18:21]
	v_mfma_f32_16x16x32_bf16 v[26:29], v[174:177], v[162:165], v[26:29]
	s_waitcnt lgkmcnt(6)
	v_mfma_f32_16x16x32_bf16 v[22:25], v[170:173], v[166:169], v[22:25]
	v_mfma_f32_16x16x32_bf16 v[30:33], v[174:177], v[166:169], v[30:33]
	ds_read_b128 v[206:209], v149 offset:4688
	ds_read_b128 v[210:213], v149 offset:6992
	ds_read_b128 v[222:225], v150 offset:41552
	ds_read_b128 v[226:229], v150 offset:43856
	s_waitcnt lgkmcnt(9)
	v_mfma_f32_16x16x32_bf16 v[34:37], v[178:181], v[154:157], v[34:37]
	v_mfma_f32_16x16x32_bf16 v[38:41], v[178:181], v[158:161], v[38:41]
	v_mfma_f32_16x16x32_bf16 v[2:5], v[178:181], v[162:165], v[2:5]
	v_mfma_f32_16x16x32_bf16 v[6:9], v[178:181], v[166:169], v[6:9]
	s_waitcnt lgkmcnt(8)
	v_mfma_f32_16x16x32_bf16 v[42:45], v[182:185], v[154:157], v[42:45]
	v_mfma_f32_16x16x32_bf16 v[46:49], v[182:185], v[158:161], v[46:49]
	v_mfma_f32_16x16x32_bf16 v[10:13], v[182:185], v[162:165], v[10:13]
	v_mfma_f32_16x16x32_bf16 v[14:17], v[182:185], v[166:169], v[14:17]
	s_waitcnt lgkmcnt(6)
	v_mfma_f32_16x16x32_bf16 v[50:53], v[214:217], v[198:201], v[50:53]
	s_waitcnt lgkmcnt(5)
	v_mfma_f32_16x16x32_bf16 v[54:57], v[214:217], v[202:205], v[54:57]
	s_waitcnt vmcnt(14)
	ds_write_b128 v146, v[98:101] offset:18448
	ds_write_b128 v146, v[102:105] offset:55312
	s_waitcnt lgkmcnt(6)
	v_mfma_f32_16x16x32_bf16 v[58:61], v[218:221], v[198:201], v[58:61]
	v_mfma_f32_16x16x32_bf16 v[62:65], v[218:221], v[202:205], v[62:65]
	s_waitcnt lgkmcnt(5)
	v_mfma_f32_16x16x32_bf16 v[18:21], v[214:217], v[206:209], v[18:21]
	v_mfma_f32_16x16x32_bf16 v[26:29], v[218:221], v[206:209], v[26:29]
	s_waitcnt vmcnt(12)
	ds_write_b128 v146, v[106:109] offset:23056
	ds_write_b128 v146, v[110:113] offset:59920
	s_waitcnt lgkmcnt(6)
	v_mfma_f32_16x16x32_bf16 v[22:25], v[214:217], v[210:213], v[22:25]
	v_mfma_f32_16x16x32_bf16 v[30:33], v[218:221], v[210:213], v[30:33]
	s_waitcnt lgkmcnt(5)
	v_mfma_f32_16x16x32_bf16 v[34:37], v[222:225], v[198:201], v[34:37]
	v_mfma_f32_16x16x32_bf16 v[38:41], v[222:225], v[202:205], v[38:41]
	s_waitcnt vmcnt(10)
	ds_write_b128 v146, v[114:117] offset:27664
	ds_write_b128 v146, v[118:121] offset:64528
	v_mfma_f32_16x16x32_bf16 v[2:5], v[222:225], v[206:209], v[2:5]
	v_mfma_f32_16x16x32_bf16 v[6:9], v[222:225], v[210:213], v[6:9]
	s_waitcnt lgkmcnt(6)
	v_mfma_f32_16x16x32_bf16 v[42:45], v[226:229], v[198:201], v[42:45]
	v_mfma_f32_16x16x32_bf16 v[46:49], v[226:229], v[202:205], v[46:49]
	s_waitcnt vmcnt(8)
	ds_write_b128 v146, v[122:125] offset:32272
	ds_write_b128 v147, v[126:129] offset:32256
	v_mfma_f32_16x16x32_bf16 v[10:13], v[226:229], v[206:209], v[10:13]
	v_mfma_f32_16x16x32_bf16 v[14:17], v[226:229], v[210:213], v[14:17]
	s_waitcnt lgkmcnt(0)
	s_barrier
	global_load_dwordx4 v[98:101], v194, s[100:101] offset:384
	global_load_dwordx4 v[102:105], v190, s[98:99] offset:384
	global_load_dwordx4 v[106:109], v195, s[100:101] offset:384
	global_load_dwordx4 v[110:113], v191, s[98:99] offset:384
	global_load_dwordx4 v[114:117], v196, s[100:101] offset:384
	global_load_dwordx4 v[118:121], v192, s[98:99] offset:384
	global_load_dwordx4 v[122:125], v197, s[100:101] offset:384
	global_load_dwordx4 v[126:129], v193, s[98:99] offset:384
	ds_read_b128 v[170:173], v150 offset:55312
	ds_read_b128 v[154:157], v149 offset:18448
	ds_read_b128 v[158:161], v149 offset:20752
	ds_read_b128 v[174:177], v150 offset:57616
	ds_read_b128 v[162:165], v149 offset:23056
	ds_read_b128 v[166:169], v149 offset:25360
	ds_read_b128 v[178:181], v150 offset:59920
	ds_read_b128 v[182:185], v150 offset:62224
	s_waitcnt lgkmcnt(6)
	v_mfma_f32_16x16x32_bf16 v[50:53], v[170:173], v[154:157], v[50:53]
	s_waitcnt lgkmcnt(5)
	v_mfma_f32_16x16x32_bf16 v[54:57], v[170:173], v[158:161], v[54:57]
	s_waitcnt lgkmcnt(4)
	v_mfma_f32_16x16x32_bf16 v[58:61], v[174:177], v[154:157], v[58:61]
	v_mfma_f32_16x16x32_bf16 v[62:65], v[174:177], v[158:161], v[62:65]
	ds_read_b128 v[214:217], v150 offset:55376
	ds_read_b128 v[198:201], v149 offset:18512
	ds_read_b128 v[202:205], v149 offset:20816
	ds_read_b128 v[218:221], v150 offset:57680
	s_waitcnt lgkmcnt(7)
	v_mfma_f32_16x16x32_bf16 v[18:21], v[170:173], v[162:165], v[18:21]
	v_mfma_f32_16x16x32_bf16 v[26:29], v[174:177], v[162:165], v[26:29]
	s_waitcnt lgkmcnt(6)
; #define MFMA(a, b, c) __builtin_amdgcn_mfma_f32_32x32x16_bf16((a), (b), (c), 0, 0, 0)
; template <bool SWAP, class Epi>
; DI void gemm_tile(const u16* __restrict__ A, int lda, const u16* __restrict__ Bt, int ldb, int K, int m0, int n0, char* smem, Epi&& epi) {
;     ...
;   auto compute = [&](int buf) __attribute__((always_inline)) {
;     bf16x8 af[2][2], bfr[2][2];
;     af[0][0] = *(const bf16x8*)(Asb + buf * 128 * 72);
;     af[0][1] = *(const bf16x8*)(Asb + buf * 128 * 72 + 32 * 72);
;     bfr[0][0] = *(const bf16x8*)(Bsb + buf * 128 * 72);
;     bfr[0][1] = *(const bf16x8*)(Bsb + buf * 128 * 72 + 32 * 72);
; #pragma unroll
;     for (int ks = 0; ks < 4; ++ks) {
;       const int c = ks & 1, n = c ^ 1;
;       if (ks < 3) {
;         af[n][0] = *(const bf16x8*)(Asb + buf * 128 * 72 + (ks + 1) * 16);
;         af[n][1] = *(const bf16x8*)(Asb + buf * 128 * 72 + 32 * 72 + (ks + 1) * 16);
;         bfr[n][0] = *(const bf16x8*)(Bsb + buf * 128 * 72 + (ks + 1) * 16);
;         bfr[n][1] = *(const bf16x8*)(Bsb + buf * 128 * 72 + 32 * 72 + (ks + 1) * 16);
;       }
;       __builtin_amdgcn_sched_barrier(0);
; #pragma unroll
;       for (int mi = 0; mi < 2; ++mi)
; #pragma unroll
;         for (int ni = 0; ni < 2; ++ni) {
;           if (SWAP) acc[mi][ni] = MFMA(bfr[c][ni], af[c][mi], acc[mi][ni]);
;           else acc[mi][ni] = MFMA(af[c][mi], bfr[c][ni], acc[mi][ni]);
;         }
;       __builtin_amdgcn_sched_barrier(0);
;     }
;   };
;   for (int kt = 0; kt < KT; kt += 2) {
;     if (kt + 2 < KT) {
;       const int k0 = (kt + 2) << 6;
; #pragma unroll
;       for (int i = 0; i < 4; ++i) { ra0[i] = *(const u32x4*)(ag + (size_t)i * 32 * lda + k0); rb0[i] = *(const u32x4*)(bg + (size_t)i * 32 * ldb + k0); }
;     }
;     compute(0);
; #pragma unroll
;     for (int i = 0; i < 4; ++i) { *(u32x4*)(asw + 128 * 72 + 32 * i * 72) = ra1[i]; *(u32x4*)(bsw + 128 * 72 + 32 * i * 72) = rb1[i]; }
;     __syncthreads();
;     if (kt + 3 < KT) {
;       const int k0 = (kt + 3) << 6;
; #pragma unroll
;       for (int i = 0; i < 4; ++i) { ra1[i] = *(const u32x4*)(ag + (size_t)i * 32 * lda + k0); rb1[i] = *(const u32x4*)(bg + (size_t)i * 32 * ldb + k0); }
;     }
;     compute(1);
;     if (kt + 2 < KT) {
; #pragma unroll
;       for (int i = 0; i < 4; ++i) { *(u32x4*)(asw + 32 * i * 72) = ra0[i]; *(u32x4*)(bsw + 32 * i * 72) = rb0[i]; }
;     }
;     __syncthreads();
;   }
	v_mfma_f32_16x16x32_bf16 v[22:25], v[170:173], v[166:169], v[22:25]
	v_mfma_f32_16x16x32_bf16 v[30:33], v[174:177], v[166:169], v[30:33]
	ds_read_b128 v[206:209], v149 offset:23120
	ds_read_b128 v[210:213], v149 offset:25424
	ds_read_b128 v[222:225], v150 offset:59984
	ds_read_b128 v[226:229], v150 offset:62288
	s_waitcnt lgkmcnt(9)
	v_mfma_f32_16x16x32_bf16 v[34:37], v[178:181], v[154:157], v[34:37]
	v_mfma_f32_16x16x32_bf16 v[38:41], v[178:181], v[158:161], v[38:41]
	v_mfma_f32_16x16x32_bf16 v[2:5], v[178:181], v[162:165], v[2:5]
	v_mfma_f32_16x16x32_bf16 v[6:9], v[178:181], v[166:169], v[6:9]
	s_waitcnt lgkmcnt(8)
	v_mfma_f32_16x16x32_bf16 v[42:45], v[182:185], v[154:157], v[42:45]
	v_mfma_f32_16x16x32_bf16 v[46:49], v[182:185], v[158:161], v[46:49]
	v_mfma_f32_16x16x32_bf16 v[10:13], v[182:185], v[162:165], v[10:13]
	v_mfma_f32_16x16x32_bf16 v[14:17], v[182:185], v[166:169], v[14:17]
	s_waitcnt lgkmcnt(6)
	v_mfma_f32_16x16x32_bf16 v[50:53], v[214:217], v[198:201], v[50:53]
	s_waitcnt lgkmcnt(5)
	v_mfma_f32_16x16x32_bf16 v[54:57], v[214:217], v[202:205], v[54:57]
	s_waitcnt vmcnt(14)
	ds_write_b128 v146, v[66:69] offset:16
	ds_write_b128 v146, v[70:73] offset:36880
	s_waitcnt lgkmcnt(6)
	v_mfma_f32_16x16x32_bf16 v[58:61], v[218:221], v[198:201], v[58:61]
	v_mfma_f32_16x16x32_bf16 v[62:65], v[218:221], v[202:205], v[62:65]
	s_waitcnt lgkmcnt(5)
	v_mfma_f32_16x16x32_bf16 v[18:21], v[214:217], v[206:209], v[18:21]
	v_mfma_f32_16x16x32_bf16 v[26:29], v[218:221], v[206:209], v[26:29]
	s_waitcnt vmcnt(12)
	ds_write_b128 v146, v[74:77] offset:4624
	ds_write_b128 v146, v[78:81] offset:41488
	s_waitcnt lgkmcnt(6)
	v_mfma_f32_16x16x32_bf16 v[22:25], v[214:217], v[210:213], v[22:25]
	v_mfma_f32_16x16x32_bf16 v[30:33], v[218:221], v[210:213], v[30:33]
	s_waitcnt lgkmcnt(5)
	v_mfma_f32_16x16x32_bf16 v[34:37], v[222:225], v[198:201], v[34:37]
	v_mfma_f32_16x16x32_bf16 v[38:41], v[222:225], v[202:205], v[38:41]
	s_waitcnt vmcnt(10)
	ds_write_b128 v146, v[82:85] offset:9232
	ds_write_b128 v146, v[86:89] offset:46096
	v_mfma_f32_16x16x32_bf16 v[2:5], v[222:225], v[206:209], v[2:5]
	v_mfma_f32_16x16x32_bf16 v[6:9], v[222:225], v[210:213], v[6:9]
	s_waitcnt lgkmcnt(6)
	v_mfma_f32_16x16x32_bf16 v[42:45], v[226:229], v[198:201], v[42:45]
	v_mfma_f32_16x16x32_bf16 v[46:49], v[226:229], v[202:205], v[46:49]
	s_waitcnt vmcnt(8)
	ds_write_b128 v146, v[90:93] offset:13840
	ds_write_b128 v146, v[94:97] offset:50704
	v_mfma_f32_16x16x32_bf16 v[10:13], v[226:229], v[206:209], v[10:13]
	v_mfma_f32_16x16x32_bf16 v[14:17], v[226:229], v[210:213], v[14:17]
	s_add_i32 s24, s24, 2
	s_add_u32 s98, s98, 256
	s_addc_u32 s99, s99, 0
	s_add_u32 s100, s100, 256
	s_addc_u32 s101, s101, 0
	s_waitcnt lgkmcnt(0)
	s_barrier
	s_cmp_lt_u32 s24, 30
	s_cbranch_scc1 .LBB0_387
	ds_read_b128 v[170:173], v150 offset:36880
	ds_read_b128 v[154:157], v149 offset:16
	ds_read_b128 v[158:161], v149 offset:2320
	ds_read_b128 v[174:177], v150 offset:39184
	ds_read_b128 v[162:165], v149 offset:4624
	ds_read_b128 v[166:169], v149 offset:6928
	ds_read_b128 v[178:181], v150 offset:41488
	ds_read_b128 v[182:185], v150 offset:43792
	s_waitcnt lgkmcnt(6)
	v_mfma_f32_16x16x32_bf16 v[50:53], v[170:173], v[154:157], v[50:53]
	s_waitcnt lgkmcnt(5)
	v_mfma_f32_16x16x32_bf16 v[54:57], v[170:173], v[158:161], v[54:57]
	s_waitcnt lgkmcnt(4)
	v_mfma_f32_16x16x32_bf16 v[58:61], v[174:177], v[154:157], v[58:61]
	v_mfma_f32_16x16x32_bf16 v[62:65], v[174:177], v[158:161], v[62:65]
	ds_read_b128 v[214:217], v150 offset:36944
	ds_read_b128 v[198:201], v149 offset:80
	ds_read_b128 v[202:205], v149 offset:2384
	ds_read_b128 v[218:221], v150 offset:39248
	s_waitcnt lgkmcnt(7)
	v_mfma_f32_16x16x32_bf16 v[18:21], v[170:173], v[162:165], v[18:21]
	v_mfma_f32_16x16x32_bf16 v[26:29], v[174:177], v[162:165], v[26:29]
	s_waitcnt lgkmcnt(6)
	v_mfma_f32_16x16x32_bf16 v[22:25], v[170:173], v[166:169], v[22:25]
	v_mfma_f32_16x16x32_bf16 v[30:33], v[174:177], v[166:169], v[30:33]
	ds_read_b128 v[206:209], v149 offset:4688
	ds_read_b128 v[210:213], v149 offset:6992
	ds_read_b128 v[222:225], v150 offset:41552
	ds_read_b128 v[226:229], v150 offset:43856
	s_waitcnt lgkmcnt(9)
	v_mfma_f32_16x16x32_bf16 v[34:37], v[178:181], v[154:157], v[34:37]
	v_mfma_f32_16x16x32_bf16 v[38:41], v[178:181], v[158:161], v[38:41]
	v_mfma_f32_16x16x32_bf16 v[2:5], v[178:181], v[162:165], v[2:5]
	v_mfma_f32_16x16x32_bf16 v[6:9], v[178:181], v[166:169], v[6:9]
	s_waitcnt lgkmcnt(8)
	v_mfma_f32_16x16x32_bf16 v[42:45], v[182:185], v[154:157], v[42:45]
	v_mfma_f32_16x16x32_bf16 v[46:49], v[182:185], v[158:161], v[46:49]
	v_mfma_f32_16x16x32_bf16 v[10:13], v[182:185], v[162:165], v[10:13]
	v_mfma_f32_16x16x32_bf16 v[14:17], v[182:185], v[166:169], v[14:17]
	s_waitcnt lgkmcnt(6)
	v_mfma_f32_16x16x32_bf16 v[50:53], v[214:217], v[198:201], v[50:53]
	s_waitcnt lgkmcnt(5)
	v_mfma_f32_16x16x32_bf16 v[54:57], v[214:217], v[202:205], v[54:57]
	s_waitcnt vmcnt(6)
	ds_write_b128 v146, v[98:101] offset:18448
	ds_write_b128 v146, v[102:105] offset:55312
	s_waitcnt lgkmcnt(6)
	v_mfma_f32_16x16x32_bf16 v[58:61], v[218:221], v[198:201], v[58:61]
	v_mfma_f32_16x16x32_bf16 v[62:65], v[218:221], v[202:205], v[62:65]
	s_waitcnt lgkmcnt(5)
	v_mfma_f32_16x16x32_bf16 v[18:21], v[214:217], v[206:209], v[18:21]
	v_mfma_f32_16x16x32_bf16 v[26:29], v[218:221], v[206:209], v[26:29]
	s_waitcnt vmcnt(4)
	ds_write_b128 v146, v[106:109] offset:23056
	ds_write_b128 v146, v[110:113] offset:59920
	s_waitcnt lgkmcnt(6)
	v_mfma_f32_16x16x32_bf16 v[22:25], v[214:217], v[210:213], v[22:25]
	v_mfma_f32_16x16x32_bf16 v[30:33], v[218:221], v[210:213], v[30:33]
	s_waitcnt lgkmcnt(5)
	v_mfma_f32_16x16x32_bf16 v[34:37], v[222:225], v[198:201], v[34:37]
	v_mfma_f32_16x16x32_bf16 v[38:41], v[222:225], v[202:205], v[38:41]
	s_waitcnt vmcnt(2)
	ds_write_b128 v146, v[114:117] offset:27664
	ds_write_b128 v146, v[118:121] offset:64528
	v_mfma_f32_16x16x32_bf16 v[2:5], v[222:225], v[206:209], v[2:5]
	v_mfma_f32_16x16x32_bf16 v[6:9], v[222:225], v[210:213], v[6:9]
	s_waitcnt lgkmcnt(6)
	v_mfma_f32_16x16x32_bf16 v[42:45], v[226:229], v[198:201], v[42:45]
	v_mfma_f32_16x16x32_bf16 v[46:49], v[226:229], v[202:205], v[46:49]
	s_waitcnt vmcnt(0)
	ds_write_b128 v146, v[122:125] offset:32272
	ds_write_b128 v147, v[126:129] offset:32256
	v_mfma_f32_16x16x32_bf16 v[10:13], v[226:229], v[206:209], v[10:13]
	v_mfma_f32_16x16x32_bf16 v[14:17], v[226:229], v[210:213], v[14:17]
	s_waitcnt lgkmcnt(0)
	s_barrier
; template <bool SWAP, class Epi>
; DI void gemm_tile(const u16* __restrict__ A, int lda, const u16* __restrict__ Bt, int ldb, int K, int m0, int n0, char* smem, Epi&& epi) {
;     ...
;   auto compute = [&](int buf) __attribute__((always_inline)) {
;     bf16x8 af[2][2], bfr[2][2];
;     af[0][0] = *(const bf16x8*)(Asb + buf * 128 * 72);
;     af[0][1] = *(const bf16x8*)(Asb + buf * 128 * 72 + 32 * 72);
;     bfr[0][0] = *(const bf16x8*)(Bsb + buf * 128 * 72);
;     bfr[0][1] = *(const bf16x8*)(Bsb + buf * 128 * 72 + 32 * 72);
; #pragma unroll
;     for (int ks = 0; ks < 4; ++ks) {
;       const int c = ks & 1, n = c ^ 1;
;       if (ks < 3) {
;         af[n][0] = *(const bf16x8*)(Asb + buf * 128 * 72 + (ks + 1) * 16);
;         af[n][1] = *(const bf16x8*)(Asb + buf * 128 * 72 + 32 * 72 + (ks + 1) * 16);
;         bfr[n][0] = *(const bf16x8*)(Bsb + buf * 128 * 72 + (ks + 1) * 16);
;         bfr[n][1] = *(const bf16x8*)(Bsb + buf * 128 * 72 + 32 * 72 + (ks + 1) * 16);
;       }
;       __builtin_amdgcn_sched_barrier(0);
; #pragma unroll
;       for (int mi = 0; mi < 2; ++mi)
; #pragma unroll
;         for (int ni = 0; ni < 2; ++ni) {
;           if (SWAP) acc[mi][ni] = MFMA(bfr[c][ni], af[c][mi], acc[mi][ni]);
;           else acc[mi][ni] = MFMA(af[c][mi], bfr[c][ni], acc[mi][ni]);
;         }
;       __builtin_amdgcn_sched_barrier(0);
;     }
;   };
;   for (int kt = 0; kt < KT; kt += 2) {
;     if (kt + 2 < KT) {
;       const int k0 = (kt + 2) << 6;
; #pragma unroll
;       for (int i = 0; i < 4; ++i) { ra0[i] = *(const u32x4*)(ag + (size_t)i * 32 * lda + k0); rb0[i] = *(const u32x4*)(bg + (size_t)i * 32 * ldb + k0); }
;     }
;     compute(0);
; #pragma unroll
;     for (int i = 0; i < 4; ++i) { *(u32x4*)(asw + 128 * 72 + 32 * i * 72) = ra1[i]; *(u32x4*)(bsw + 128 * 72 + 32 * i * 72) = rb1[i]; }
;     __syncthreads();
;     if (kt + 3 < KT) {
;       const int k0 = (kt + 3) << 6;
; #pragma unroll
;       for (int i = 0; i < 4; ++i) { ra1[i] = *(const u32x4*)(ag + (size_t)i * 32 * lda + k0); rb1[i] = *(const u32x4*)(bg + (size_t)i * 32 * ldb + k0); }
;     }
;     compute(1);
;     if (kt + 2 < KT) {
; #pragma unroll
;       for (int i = 0; i < 4; ++i) { *(u32x4*)(asw + 32 * i * 72) = ra0[i]; *(u32x4*)(bsw + 32 * i * 72) = rb0[i]; }
;     }
;     __syncthreads();
;   }
;   epi(acc, m0 + wm * 64, n0 + wn * 64, r, hi);
	ds_read_b128 v[170:173], v150 offset:55312
	ds_read_b128 v[154:157], v149 offset:18448
	ds_read_b128 v[158:161], v149 offset:20752
	ds_read_b128 v[174:177], v150 offset:57616
	ds_read_b128 v[162:165], v149 offset:23056
	ds_read_b128 v[166:169], v149 offset:25360
	ds_read_b128 v[178:181], v150 offset:59920
	ds_read_b128 v[182:185], v150 offset:62224
	s_waitcnt lgkmcnt(6)
	v_mfma_f32_16x16x32_bf16 v[50:53], v[170:173], v[154:157], v[50:53]
	s_waitcnt lgkmcnt(5)
	v_mfma_f32_16x16x32_bf16 v[54:57], v[170:173], v[158:161], v[54:57]
	s_waitcnt lgkmcnt(4)
	v_mfma_f32_16x16x32_bf16 v[58:61], v[174:177], v[154:157], v[58:61]
	v_mfma_f32_16x16x32_bf16 v[62:65], v[174:177], v[158:161], v[62:65]
	ds_read_b128 v[214:217], v150 offset:55376
	ds_read_b128 v[198:201], v149 offset:18512
	ds_read_b128 v[202:205], v149 offset:20816
	ds_read_b128 v[218:221], v150 offset:57680
	s_waitcnt lgkmcnt(7)
	v_mfma_f32_16x16x32_bf16 v[18:21], v[170:173], v[162:165], v[18:21]
	v_mfma_f32_16x16x32_bf16 v[26:29], v[174:177], v[162:165], v[26:29]
	s_waitcnt lgkmcnt(6)
	v_mfma_f32_16x16x32_bf16 v[22:25], v[170:173], v[166:169], v[22:25]
	v_mfma_f32_16x16x32_bf16 v[30:33], v[174:177], v[166:169], v[30:33]
	ds_read_b128 v[206:209], v149 offset:23120
	ds_read_b128 v[210:213], v149 offset:25424
	ds_read_b128 v[222:225], v150 offset:59984
	ds_read_b128 v[226:229], v150 offset:62288
	s_waitcnt lgkmcnt(9)
	v_mfma_f32_16x16x32_bf16 v[34:37], v[178:181], v[154:157], v[34:37]
	v_mfma_f32_16x16x32_bf16 v[38:41], v[178:181], v[158:161], v[38:41]
	v_mfma_f32_16x16x32_bf16 v[2:5], v[178:181], v[162:165], v[2:5]
	v_mfma_f32_16x16x32_bf16 v[6:9], v[178:181], v[166:169], v[6:9]
	s_waitcnt lgkmcnt(8)
	v_mfma_f32_16x16x32_bf16 v[42:45], v[182:185], v[154:157], v[42:45]
	v_mfma_f32_16x16x32_bf16 v[46:49], v[182:185], v[158:161], v[46:49]
	v_mfma_f32_16x16x32_bf16 v[10:13], v[182:185], v[162:165], v[10:13]
	v_mfma_f32_16x16x32_bf16 v[14:17], v[182:185], v[166:169], v[14:17]
	s_waitcnt lgkmcnt(6)
	v_mfma_f32_16x16x32_bf16 v[50:53], v[214:217], v[198:201], v[50:53]
	s_waitcnt lgkmcnt(5)
	v_mfma_f32_16x16x32_bf16 v[54:57], v[214:217], v[202:205], v[54:57]
	s_waitcnt lgkmcnt(4)
	v_mfma_f32_16x16x32_bf16 v[58:61], v[218:221], v[198:201], v[58:61]
	v_mfma_f32_16x16x32_bf16 v[62:65], v[218:221], v[202:205], v[62:65]
	s_waitcnt lgkmcnt(3)
	v_mfma_f32_16x16x32_bf16 v[18:21], v[214:217], v[206:209], v[18:21]
	v_mfma_f32_16x16x32_bf16 v[26:29], v[218:221], v[206:209], v[26:29]
	s_waitcnt lgkmcnt(2)
	v_mfma_f32_16x16x32_bf16 v[22:25], v[214:217], v[210:213], v[22:25]
	v_mfma_f32_16x16x32_bf16 v[30:33], v[218:221], v[210:213], v[30:33]
	s_waitcnt lgkmcnt(1)
	v_mfma_f32_16x16x32_bf16 v[34:37], v[222:225], v[198:201], v[34:37]
	v_mfma_f32_16x16x32_bf16 v[38:41], v[222:225], v[202:205], v[38:41]
	v_mfma_f32_16x16x32_bf16 v[2:5], v[222:225], v[206:209], v[2:5]
	v_mfma_f32_16x16x32_bf16 v[6:9], v[222:225], v[210:213], v[6:9]
	s_waitcnt lgkmcnt(0)
	v_mfma_f32_16x16x32_bf16 v[42:45], v[226:229], v[198:201], v[42:45]
	v_mfma_f32_16x16x32_bf16 v[46:49], v[226:229], v[202:205], v[46:49]
	v_mfma_f32_16x16x32_bf16 v[10:13], v[226:229], v[206:209], v[10:13]
	v_mfma_f32_16x16x32_bf16 v[14:17], v[226:229], v[210:213], v[14:17]
	s_nop 7
	s_nop 7
	v_permlane16_swap_b32_e32 v50, v54
	v_permlane16_swap_b32_e32 v51, v55
	v_permlane16_swap_b32_e32 v52, v56
	v_permlane16_swap_b32_e32 v53, v57
	v_permlane16_swap_b32_e32 v58, v62
	v_permlane16_swap_b32_e32 v59, v63
	v_permlane16_swap_b32_e32 v60, v64
	v_permlane16_swap_b32_e32 v61, v65
	v_permlane16_swap_b32_e32 v34, v38
	v_permlane16_swap_b32_e32 v35, v39
	v_permlane16_swap_b32_e32 v36, v40
	v_permlane16_swap_b32_e32 v37, v41
	v_permlane16_swap_b32_e32 v42, v46
	v_permlane16_swap_b32_e32 v43, v47
	v_permlane16_swap_b32_e32 v44, v48
	v_permlane16_swap_b32_e32 v45, v49
	v_permlane16_swap_b32_e32 v18, v22
	v_permlane16_swap_b32_e32 v19, v23
	v_permlane16_swap_b32_e32 v20, v24
	v_permlane16_swap_b32_e32 v21, v25
	v_permlane16_swap_b32_e32 v26, v30
	v_permlane16_swap_b32_e32 v27, v31
	v_permlane16_swap_b32_e32 v28, v32
	v_permlane16_swap_b32_e32 v29, v33
	v_permlane16_swap_b32_e32 v2, v6
	v_permlane16_swap_b32_e32 v3, v7
	v_permlane16_swap_b32_e32 v4, v8
	v_permlane16_swap_b32_e32 v5, v9
	v_permlane16_swap_b32_e32 v10, v14
	v_permlane16_swap_b32_e32 v11, v15
	v_permlane16_swap_b32_e32 v12, v16
	v_permlane16_swap_b32_e32 v13, v17
	v_permlane32_swap_b32_e32 v50, v54
	v_permlane32_swap_b32_e32 v51, v55
	v_permlane32_swap_b32_e32 v52, v56
	v_permlane32_swap_b32_e32 v53, v57
	v_permlane32_swap_b32_e32 v58, v62
	v_permlane32_swap_b32_e32 v59, v63
	v_permlane32_swap_b32_e32 v60, v64
	v_permlane32_swap_b32_e32 v61, v65
	v_permlane32_swap_b32_e32 v34, v38
	v_permlane32_swap_b32_e32 v35, v39
	v_permlane32_swap_b32_e32 v36, v40
	v_permlane32_swap_b32_e32 v37, v41
	v_permlane32_swap_b32_e32 v42, v46
	v_permlane32_swap_b32_e32 v43, v47
	v_permlane32_swap_b32_e32 v44, v48
	v_permlane32_swap_b32_e32 v45, v49
	v_permlane32_swap_b32_e32 v18, v22
	v_permlane32_swap_b32_e32 v19, v23
	v_permlane32_swap_b32_e32 v20, v24
	v_permlane32_swap_b32_e32 v21, v25
	v_permlane32_swap_b32_e32 v26, v30
	v_permlane32_swap_b32_e32 v27, v31
	v_permlane32_swap_b32_e32 v28, v32
	v_permlane32_swap_b32_e32 v29, v33
	v_permlane32_swap_b32_e32 v2, v6
	v_permlane32_swap_b32_e32 v3, v7
	v_permlane32_swap_b32_e32 v4, v8
	v_permlane32_swap_b32_e32 v5, v9
	v_permlane32_swap_b32_e32 v10, v14
	v_permlane32_swap_b32_e32 v11, v15
	v_permlane32_swap_b32_e32 v12, v16
	v_permlane32_swap_b32_e32 v13, v17
	s_waitcnt lgkmcnt(0)
	s_barrier
	s_branch .LBB0_393

; template <bool SWAP, class Epi>
; DI void gemm_tile(const u16* __restrict__ A, int lda, const u16* __restrict__ Bt, int ldb, int K, int m0, int n0, char* smem, Epi&& epi) {
;     ...
;   const int tid = threadIdx.x, lane = tid & 63, w = tid >> 6, wm = w >> 1, wn = w & 1;
;   const int r = lane & 31, hi = lane >> 5;
;   f32x16 acc[2][2];
; #pragma unroll
;   for (int a = 0; a < 2; ++a)
; #pragma unroll
;     for (int b = 0; b < 2; ++b)
; #pragma unroll
;       for (int i = 0; i < 16; ++i) acc[a][b][i] = 0.f;
;   const int srow = tid >> 3, skc = tid & 7;
;   const u16* ag = A + (size_t)(m0 + srow) * lda + skc * 8;
;   const u16* bg = Bt + (size_t)(n0 + srow) * ldb + skc * 8;
;   u16* asw = As + srow * 72 + skc * 8;
;   u16* bsw = Bs + srow * 72 + skc * 8;
;   u32x4 ra0[4], rb0[4], ra1[4], rb1[4];
; #pragma unroll
;   for (int i = 0; i < 4; ++i) { ra0[i] = *(const u32x4*)(ag + (size_t)i * 32 * lda); rb0[i] = *(const u32x4*)(bg + (size_t)i * 32 * ldb); }
; #pragma unroll
;   for (int i = 0; i < 4; ++i) { ra1[i] = *(const u32x4*)(ag + (size_t)i * 32 * lda + 64); rb1[i] = *(const u32x4*)(bg + (size_t)i * 32 * ldb + 64); }
;   __syncthreads();
; #pragma unroll
;   for (int i = 0; i < 4; ++i) { *(u32x4*)(asw + 32 * i * 72) = ra0[i]; *(u32x4*)(bsw + 32 * i * 72) = rb0[i]; }
;   __syncthreads();
;   const int KT = K >> 6;
;   const u16* Asb = As + (wm * 64 + r) * 72 + hi * 8;
;   const u16* Bsb = Bs + (wn * 64 + r) * 72 + hi * 8;
; DI void phase5(const Params& p, char* smem) {
;     ...
;   for (int it = blockIdx.x; it < 64 * 16; it += gridDim.x) {
;     const int tn = it / 64, tm = it % 64;
;     gemm_tile<true>(MG, D_, W, D_, D_, tm * 128, tn * 128, smem, [&](f32x16 (&acc)[2][2], int mb, int nb, int r, int hi) __attribute__((always_inline)) {
.Lprio_p5:
	s_cmpk_gt_i32 s12, 0x3ff
	s_cbranch_scc1 .LBB0_754
	s_waitcnt lgkmcnt(0)
	v_lshlrev_b32_e32 v2, 4, v0
	v_and_b32_e32 v130, 0x70, v2
	v_mov_b32_e32 v131, 0
	v_lshl_add_u64 v[2:3], s[82:83], 0, v[130:131]
	s_mov_b64 s[4:5], 0x10638000
	v_lshrrev_b32_e32 v1, 3, v0
	s_waitcnt vmcnt(9)
	v_lshl_add_u64 v[132:133], v[2:3], 0, s[4:5]
	s_mov_b64 s[4:5], 0x14b8000
	v_lshl_add_u64 v[134:135], v[2:3], 0, s[4:5]
	v_mul_u32_u24_e32 v2, 0x48, v1
	v_and_b32_e32 v4, 31, v0
	v_lshlrev_b32_e32 v2, 1, v2
	v_lshrrev_b32_e32 v3, 1, v0
	s_waitcnt vmcnt(6)
	v_add3_u32 v144, 0, v2, v130
	v_bfe_u32 v2, v0, 5, 1
	v_and_or_b32 v146, v3, 64, v4
	v_mul_u32_u24_e32 v3, 0x90, v146
	v_lshlrev_b32_e32 v4, 4, v2
	v_add3_u32 v147, 0, v3, v4
	v_and_b32_e32 v3, 0x5f, v0
	s_load_dword s13, s[0:1], 0xc0
	v_mul_u32_u24_e32 v3, 0x90, v3
	s_waitcnt vmcnt(5)
	v_add3_u32 v148, 0, v3, v4
	v_and_b32_e32 v3, 64, v0
	s_add_u32 s2, s82, 0x12638000
	v_lshl_or_b32 v149, v2, 2, v3
	v_and_b32_e32 v2, 7, v0
	s_addc_u32 s3, s83, 0
	v_add_u32_e32 v145, 0x9010, v144
	v_lshlrev_b32_e32 v130, 4, v2
	s_mov_b32 s14, 0x20000
	s_mov_b32 s15, 0x40000
	s_mov_b32 s16, 0x60000
	s_mov_b64 s[4:5], 0x100
	s_mov_b64 s[6:7], 0xc000
	s_mov_b32 s17, s12
	v_lshrrev_b32_e32 v198, 3, v0
	v_lshrrev_b32_e32 v199, 2, v198
	v_lshrrev_b32_e32 v200, 3, v198
	v_xor_b32_e32 v199, v199, v200
	v_and_b32_e32 v199, 1, v199
	v_and_b32_e32 v200, 1, v0
	v_lshlrev_b32_e32 v200, 5, v200
	v_sub_u32_e32 v200, 16, v200
	v_mul_lo_u32 v199, v199, v200
	v_add_u32_e32 v144, v144, v199
	v_add_u32_e32 v145, v145, v199
	v_and_b32_e32 v198, 15, v0
	v_bfe_u32 v199, v0, 4, 2
	v_lshrrev_b32_e32 v200, 2, v198
	v_lshrrev_b32_e32 v201, 3, v198
	v_xor_b32_e32 v200, v200, v201
	v_and_b32_e32 v200, 1, v200
	v_xor_b32_e32 v199, v199, v200
	v_lshlrev_b32_e32 v199, 4, v199
	v_bfe_u32 v200, v0, 7, 1
	v_lshl_or_b32 v200, v200, 6, v198
	v_mul_u32_u24_e32 v200, 0x90, v200
	v_add_u32_e32 v147, v200, v199
	v_bfe_u32 v200, v0, 6, 1
	v_lshl_or_b32 v200, v200, 6, v198
	v_mul_u32_u24_e32 v200, 0x90, v200
	v_add_u32_e32 v148, v200, v199
	s_branch .LBB0_746

; #define MFMA(a, b, c) __builtin_amdgcn_mfma_f32_32x32x16_bf16((a), (b), (c), 0, 0, 0)
; template <bool SWAP, class Epi>
; DI void gemm_tile(const u16* __restrict__ A, int lda, const u16* __restrict__ Bt, int ldb, int K, int m0, int n0, char* smem, Epi&& epi) {
;     ...
;   auto compute = [&](int buf) __attribute__((always_inline)) {
;     bf16x8 af[2][2], bfr[2][2];
;     af[0][0] = *(const bf16x8*)(Asb + buf * 128 * 72);
;     af[0][1] = *(const bf16x8*)(Asb + buf * 128 * 72 + 32 * 72);
;     bfr[0][0] = *(const bf16x8*)(Bsb + buf * 128 * 72);
;     bfr[0][1] = *(const bf16x8*)(Bsb + buf * 128 * 72 + 32 * 72);
; #pragma unroll
;     for (int ks = 0; ks < 4; ++ks) {
;       const int c = ks & 1, n = c ^ 1;
;       if (ks < 3) {
;         af[n][0] = *(const bf16x8*)(Asb + buf * 128 * 72 + (ks + 1) * 16);
;         af[n][1] = *(const bf16x8*)(Asb + buf * 128 * 72 + 32 * 72 + (ks + 1) * 16);
;         bfr[n][0] = *(const bf16x8*)(Bsb + buf * 128 * 72 + (ks + 1) * 16);
;         bfr[n][1] = *(const bf16x8*)(Bsb + buf * 128 * 72 + 32 * 72 + (ks + 1) * 16);
;       }
;       __builtin_amdgcn_sched_barrier(0);
; #pragma unroll
;       for (int mi = 0; mi < 2; ++mi)
; #pragma unroll
;         for (int ni = 0; ni < 2; ++ni) {
;           if (SWAP) acc[mi][ni] = MFMA(bfr[c][ni], af[c][mi], acc[mi][ni]);
;           else acc[mi][ni] = MFMA(af[c][mi], bfr[c][ni], acc[mi][ni]);
;         }
;       __builtin_amdgcn_sched_barrier(0);
;     }
;   };
;   for (int kt = 0; kt < KT; kt += 2) {
;     if (kt + 2 < KT) {
;       const int k0 = (kt + 2) << 6;
; #pragma unroll
;       for (int i = 0; i < 4; ++i) { ra0[i] = *(const u32x4*)(ag + (size_t)i * 32 * lda + k0); rb0[i] = *(const u32x4*)(bg + (size_t)i * 32 * ldb + k0); }
;     }
;     compute(0);
; #pragma unroll
;     for (int i = 0; i < 4; ++i) { *(u32x4*)(asw + 128 * 72 + 32 * i * 72) = ra1[i]; *(u32x4*)(bsw + 128 * 72 + 32 * i * 72) = rb1[i]; }
;     __syncthreads();
;     if (kt + 3 < KT) {
;       const int k0 = (kt + 3) << 6;
; #pragma unroll
;       for (int i = 0; i < 4; ++i) { ra1[i] = *(const u32x4*)(ag + (size_t)i * 32 * lda + k0); rb1[i] = *(const u32x4*)(bg + (size_t)i * 32 * ldb + k0); }
;     }
;     compute(1);
;     if (kt + 2 < KT) {
; #pragma unroll
;       for (int i = 0; i < 4; ++i) { *(u32x4*)(asw + 32 * i * 72) = ra0[i]; *(u32x4*)(bsw + 32 * i * 72) = rb0[i]; }
;     }
;     __syncthreads();
;   }
.LBB0_748:
	global_load_dwordx4 v[66:69], v194, s[100:101] offset:256
	global_load_dwordx4 v[70:73], v190, s[98:99] offset:256
	global_load_dwordx4 v[74:77], v195, s[100:101] offset:256
	global_load_dwordx4 v[78:81], v191, s[98:99] offset:256
	global_load_dwordx4 v[82:85], v196, s[100:101] offset:256
	global_load_dwordx4 v[86:89], v192, s[98:99] offset:256
	global_load_dwordx4 v[90:93], v197, s[100:101] offset:256
	global_load_dwordx4 v[94:97], v193, s[98:99] offset:256
	ds_read_b128 v[166:169], v148 offset:36880
	ds_read_b128 v[150:153], v147 offset:16
	ds_read_b128 v[154:157], v147 offset:2320
	ds_read_b128 v[170:173], v148 offset:39184
	ds_read_b128 v[158:161], v147 offset:4624
	ds_read_b128 v[162:165], v147 offset:6928
	ds_read_b128 v[174:177], v148 offset:41488
	ds_read_b128 v[178:181], v148 offset:43792
	s_waitcnt lgkmcnt(6)
	v_mfma_f32_16x16x32_bf16 v[50:53], v[166:169], v[150:153], v[50:53]
	s_waitcnt lgkmcnt(5)
	v_mfma_f32_16x16x32_bf16 v[54:57], v[166:169], v[154:157], v[54:57]
	s_waitcnt lgkmcnt(4)
	v_mfma_f32_16x16x32_bf16 v[58:61], v[170:173], v[150:153], v[58:61]
	v_mfma_f32_16x16x32_bf16 v[62:65], v[170:173], v[154:157], v[62:65]
	ds_read_b128 v[214:217], v148 offset:36944
	ds_read_b128 v[198:201], v147 offset:80
	ds_read_b128 v[202:205], v147 offset:2384
	ds_read_b128 v[218:221], v148 offset:39248
	s_waitcnt lgkmcnt(7)
	v_mfma_f32_16x16x32_bf16 v[18:21], v[166:169], v[158:161], v[18:21]
	v_mfma_f32_16x16x32_bf16 v[26:29], v[170:173], v[158:161], v[26:29]
	s_waitcnt lgkmcnt(6)
	v_mfma_f32_16x16x32_bf16 v[22:25], v[166:169], v[162:165], v[22:25]
	v_mfma_f32_16x16x32_bf16 v[30:33], v[170:173], v[162:165], v[30:33]
	ds_read_b128 v[206:209], v147 offset:4688
	ds_read_b128 v[210:213], v147 offset:6992
	ds_read_b128 v[222:225], v148 offset:41552
	ds_read_b128 v[226:229], v148 offset:43856
	s_waitcnt lgkmcnt(9)
	v_mfma_f32_16x16x32_bf16 v[34:37], v[174:177], v[150:153], v[34:37]
	v_mfma_f32_16x16x32_bf16 v[38:41], v[174:177], v[154:157], v[38:41]
	v_mfma_f32_16x16x32_bf16 v[2:5], v[174:177], v[158:161], v[2:5]
	v_mfma_f32_16x16x32_bf16 v[6:9], v[174:177], v[162:165], v[6:9]
	s_waitcnt lgkmcnt(8)
	v_mfma_f32_16x16x32_bf16 v[42:45], v[178:181], v[150:153], v[42:45]
	v_mfma_f32_16x16x32_bf16 v[46:49], v[178:181], v[154:157], v[46:49]
	v_mfma_f32_16x16x32_bf16 v[10:13], v[178:181], v[158:161], v[10:13]
	v_mfma_f32_16x16x32_bf16 v[14:17], v[178:181], v[162:165], v[14:17]
	s_waitcnt lgkmcnt(6)
	v_mfma_f32_16x16x32_bf16 v[50:53], v[214:217], v[198:201], v[50:53]
	s_waitcnt lgkmcnt(5)
	v_mfma_f32_16x16x32_bf16 v[54:57], v[214:217], v[202:205], v[54:57]
	s_waitcnt vmcnt(14)
	ds_write_b128 v144, v[98:101] offset:18448
	ds_write_b128 v144, v[102:105] offset:55312
	s_waitcnt lgkmcnt(6)
	v_mfma_f32_16x16x32_bf16 v[58:61], v[218:221], v[198:201], v[58:61]
	v_mfma_f32_16x16x32_bf16 v[62:65], v[218:221], v[202:205], v[62:65]
	s_waitcnt lgkmcnt(5)
	v_mfma_f32_16x16x32_bf16 v[18:21], v[214:217], v[206:209], v[18:21]
	v_mfma_f32_16x16x32_bf16 v[26:29], v[218:221], v[206:209], v[26:29]
	s_waitcnt vmcnt(12)
	ds_write_b128 v144, v[106:109] offset:23056
	ds_write_b128 v144, v[110:113] offset:59920
	s_waitcnt lgkmcnt(6)
	v_mfma_f32_16x16x32_bf16 v[22:25], v[214:217], v[210:213], v[22:25]
	v_mfma_f32_16x16x32_bf16 v[30:33], v[218:221], v[210:213], v[30:33]
	s_waitcnt lgkmcnt(5)
	v_mfma_f32_16x16x32_bf16 v[34:37], v[222:225], v[198:201], v[34:37]
	v_mfma_f32_16x16x32_bf16 v[38:41], v[222:225], v[202:205], v[38:41]
	s_waitcnt vmcnt(10)
	ds_write_b128 v144, v[114:117] offset:27664
	ds_write_b128 v144, v[118:121] offset:64528
	v_mfma_f32_16x16x32_bf16 v[2:5], v[222:225], v[206:209], v[2:5]
	v_mfma_f32_16x16x32_bf16 v[6:9], v[222:225], v[210:213], v[6:9]
	s_waitcnt lgkmcnt(6)
	v_mfma_f32_16x16x32_bf16 v[42:45], v[226:229], v[198:201], v[42:45]
	v_mfma_f32_16x16x32_bf16 v[46:49], v[226:229], v[202:205], v[46:49]
	s_waitcnt vmcnt(8)
	ds_write_b128 v144, v[122:125] offset:32272
	ds_write_b128 v145, v[126:129] offset:32256
	v_mfma_f32_16x16x32_bf16 v[10:13], v[226:229], v[206:209], v[10:13]
	v_mfma_f32_16x16x32_bf16 v[14:17], v[226:229], v[210:213], v[14:17]
	s_waitcnt lgkmcnt(0)
	s_barrier
	global_load_dwordx4 v[98:101], v194, s[100:101] offset:384
	global_load_dwordx4 v[102:105], v190, s[98:99] offset:384
	global_load_dwordx4 v[106:109], v195, s[100:101] offset:384
	global_load_dwordx4 v[110:113], v191, s[98:99] offset:384
	global_load_dwordx4 v[114:117], v196, s[100:101] offset:384
	global_load_dwordx4 v[118:121], v192, s[98:99] offset:384
	global_load_dwordx4 v[122:125], v197, s[100:101] offset:384
	global_load_dwordx4 v[126:129], v193, s[98:99] offset:384
	ds_read_b128 v[166:169], v148 offset:55312
	ds_read_b128 v[150:153], v147 offset:18448
	ds_read_b128 v[154:157], v147 offset:20752
	ds_read_b128 v[170:173], v148 offset:57616
	ds_read_b128 v[158:161], v147 offset:23056
	ds_read_b128 v[162:165], v147 offset:25360
	ds_read_b128 v[174:177], v148 offset:59920
	ds_read_b128 v[178:181], v148 offset:62224
	s_waitcnt lgkmcnt(6)
	v_mfma_f32_16x16x32_bf16 v[50:53], v[166:169], v[150:153], v[50:53]
	s_waitcnt lgkmcnt(5)
	v_mfma_f32_16x16x32_bf16 v[54:57], v[166:169], v[154:157], v[54:57]
	s_waitcnt lgkmcnt(4)
	v_mfma_f32_16x16x32_bf16 v[58:61], v[170:173], v[150:153], v[58:61]
	v_mfma_f32_16x16x32_bf16 v[62:65], v[170:173], v[154:157], v[62:65]
	ds_read_b128 v[214:217], v148 offset:55376
	ds_read_b128 v[198:201], v147 offset:18512
	ds_read_b128 v[202:205], v147 offset:20816
	ds_read_b128 v[218:221], v148 offset:57680
	s_waitcnt lgkmcnt(7)
	v_mfma_f32_16x16x32_bf16 v[18:21], v[166:169], v[158:161], v[18:21]
	v_mfma_f32_16x16x32_bf16 v[26:29], v[170:173], v[158:161], v[26:29]
	s_waitcnt lgkmcnt(6)
; #define MFMA(a, b, c) __builtin_amdgcn_mfma_f32_32x32x16_bf16((a), (b), (c), 0, 0, 0)
; template <bool SWAP, class Epi>
; DI void gemm_tile(const u16* __restrict__ A, int lda, const u16* __restrict__ Bt, int ldb, int K, int m0, int n0, char* smem, Epi&& epi) {
;     ...
;   auto compute = [&](int buf) __attribute__((always_inline)) {
;     bf16x8 af[2][2], bfr[2][2];
;     af[0][0] = *(const bf16x8*)(Asb + buf * 128 * 72);
;     af[0][1] = *(const bf16x8*)(Asb + buf * 128 * 72 + 32 * 72);
;     bfr[0][0] = *(const bf16x8*)(Bsb + buf * 128 * 72);
;     bfr[0][1] = *(const bf16x8*)(Bsb + buf * 128 * 72 + 32 * 72);
; #pragma unroll
;     for (int ks = 0; ks < 4; ++ks) {
;       const int c = ks & 1, n = c ^ 1;
;       if (ks < 3) {
;         af[n][0] = *(const bf16x8*)(Asb + buf * 128 * 72 + (ks + 1) * 16);
;         af[n][1] = *(const bf16x8*)(Asb + buf * 128 * 72 + 32 * 72 + (ks + 1) * 16);
;         bfr[n][0] = *(const bf16x8*)(Bsb + buf * 128 * 72 + (ks + 1) * 16);
;         bfr[n][1] = *(const bf16x8*)(Bsb + buf * 128 * 72 + 32 * 72 + (ks + 1) * 16);
;       }
;       __builtin_amdgcn_sched_barrier(0);
; #pragma unroll
;       for (int mi = 0; mi < 2; ++mi)
; #pragma unroll
;         for (int ni = 0; ni < 2; ++ni) {
;           if (SWAP) acc[mi][ni] = MFMA(bfr[c][ni], af[c][mi], acc[mi][ni]);
;           else acc[mi][ni] = MFMA(af[c][mi], bfr[c][ni], acc[mi][ni]);
;         }
;       __builtin_amdgcn_sched_barrier(0);
;     }
;   };
;   for (int kt = 0; kt < KT; kt += 2) {
;     if (kt + 2 < KT) {
;       const int k0 = (kt + 2) << 6;
; #pragma unroll
;       for (int i = 0; i < 4; ++i) { ra0[i] = *(const u32x4*)(ag + (size_t)i * 32 * lda + k0); rb0[i] = *(const u32x4*)(bg + (size_t)i * 32 * ldb + k0); }
;     }
;     compute(0);
; #pragma unroll
;     for (int i = 0; i < 4; ++i) { *(u32x4*)(asw + 128 * 72 + 32 * i * 72) = ra1[i]; *(u32x4*)(bsw + 128 * 72 + 32 * i * 72) = rb1[i]; }
;     __syncthreads();
;     if (kt + 3 < KT) {
;       const int k0 = (kt + 3) << 6;
; #pragma unroll
;       for (int i = 0; i < 4; ++i) { ra1[i] = *(const u32x4*)(ag + (size_t)i * 32 * lda + k0); rb1[i] = *(const u32x4*)(bg + (size_t)i * 32 * ldb + k0); }
;     }
;     compute(1);
;     if (kt + 2 < KT) {
; #pragma unroll
;       for (int i = 0; i < 4; ++i) { *(u32x4*)(asw + 32 * i * 72) = ra0[i]; *(u32x4*)(bsw + 32 * i * 72) = rb0[i]; }
;     }
;     __syncthreads();
;   }
	v_mfma_f32_16x16x32_bf16 v[22:25], v[166:169], v[162:165], v[22:25]
	v_mfma_f32_16x16x32_bf16 v[30:33], v[170:173], v[162:165], v[30:33]
	ds_read_b128 v[206:209], v147 offset:23120
	ds_read_b128 v[210:213], v147 offset:25424
	ds_read_b128 v[222:225], v148 offset:59984
	ds_read_b128 v[226:229], v148 offset:62288
	s_waitcnt lgkmcnt(9)
	v_mfma_f32_16x16x32_bf16 v[34:37], v[174:177], v[150:153], v[34:37]
	v_mfma_f32_16x16x32_bf16 v[38:41], v[174:177], v[154:157], v[38:41]
	v_mfma_f32_16x16x32_bf16 v[2:5], v[174:177], v[158:161], v[2:5]
	v_mfma_f32_16x16x32_bf16 v[6:9], v[174:177], v[162:165], v[6:9]
	s_waitcnt lgkmcnt(8)
	v_mfma_f32_16x16x32_bf16 v[42:45], v[178:181], v[150:153], v[42:45]
	v_mfma_f32_16x16x32_bf16 v[46:49], v[178:181], v[154:157], v[46:49]
	v_mfma_f32_16x16x32_bf16 v[10:13], v[178:181], v[158:161], v[10:13]
	v_mfma_f32_16x16x32_bf16 v[14:17], v[178:181], v[162:165], v[14:17]
	s_waitcnt lgkmcnt(6)
	v_mfma_f32_16x16x32_bf16 v[50:53], v[214:217], v[198:201], v[50:53]
	s_waitcnt lgkmcnt(5)
	v_mfma_f32_16x16x32_bf16 v[54:57], v[214:217], v[202:205], v[54:57]
	s_waitcnt vmcnt(14)
	ds_write_b128 v144, v[66:69] offset:16
	ds_write_b128 v144, v[70:73] offset:36880
	s_waitcnt lgkmcnt(6)
	v_mfma_f32_16x16x32_bf16 v[58:61], v[218:221], v[198:201], v[58:61]
	v_mfma_f32_16x16x32_bf16 v[62:65], v[218:221], v[202:205], v[62:65]
	s_waitcnt lgkmcnt(5)
	v_mfma_f32_16x16x32_bf16 v[18:21], v[214:217], v[206:209], v[18:21]
	v_mfma_f32_16x16x32_bf16 v[26:29], v[218:221], v[206:209], v[26:29]
	s_waitcnt vmcnt(12)
	ds_write_b128 v144, v[74:77] offset:4624
	ds_write_b128 v144, v[78:81] offset:41488
	s_waitcnt lgkmcnt(6)
	v_mfma_f32_16x16x32_bf16 v[22:25], v[214:217], v[210:213], v[22:25]
	v_mfma_f32_16x16x32_bf16 v[30:33], v[218:221], v[210:213], v[30:33]
	s_waitcnt lgkmcnt(5)
	v_mfma_f32_16x16x32_bf16 v[34:37], v[222:225], v[198:201], v[34:37]
	v_mfma_f32_16x16x32_bf16 v[38:41], v[222:225], v[202:205], v[38:41]
	s_waitcnt vmcnt(10)
	ds_write_b128 v144, v[82:85] offset:9232
	ds_write_b128 v144, v[86:89] offset:46096
	v_mfma_f32_16x16x32_bf16 v[2:5], v[222:225], v[206:209], v[2:5]
	v_mfma_f32_16x16x32_bf16 v[6:9], v[222:225], v[210:213], v[6:9]
	s_waitcnt lgkmcnt(6)
	v_mfma_f32_16x16x32_bf16 v[42:45], v[226:229], v[198:201], v[42:45]
	v_mfma_f32_16x16x32_bf16 v[46:49], v[226:229], v[202:205], v[46:49]
	s_waitcnt vmcnt(8)
	ds_write_b128 v144, v[90:93] offset:13840
	ds_write_b128 v144, v[94:97] offset:50704
	v_mfma_f32_16x16x32_bf16 v[10:13], v[226:229], v[206:209], v[10:13]
	v_mfma_f32_16x16x32_bf16 v[14:17], v[226:229], v[210:213], v[14:17]
	s_add_i32 s20, s20, 2
	s_add_u32 s98, s98, 256
	s_addc_u32 s99, s99, 0
	s_add_u32 s100, s100, 256
	s_addc_u32 s101, s101, 0
	s_waitcnt lgkmcnt(0)
	s_barrier
	s_cmp_lt_u32 s20, 30
	s_cbranch_scc1 .LBB0_748
	ds_read_b128 v[166:169], v148 offset:36880
	ds_read_b128 v[150:153], v147 offset:16
	ds_read_b128 v[154:157], v147 offset:2320
	ds_read_b128 v[170:173], v148 offset:39184
	ds_read_b128 v[158:161], v147 offset:4624
	ds_read_b128 v[162:165], v147 offset:6928
	ds_read_b128 v[174:177], v148 offset:41488
	ds_read_b128 v[178:181], v148 offset:43792
	s_waitcnt lgkmcnt(6)
	v_mfma_f32_16x16x32_bf16 v[50:53], v[166:169], v[150:153], v[50:53]
	s_waitcnt lgkmcnt(5)
	v_mfma_f32_16x16x32_bf16 v[54:57], v[166:169], v[154:157], v[54:57]
	s_waitcnt lgkmcnt(4)
	v_mfma_f32_16x16x32_bf16 v[58:61], v[170:173], v[150:153], v[58:61]
	v_mfma_f32_16x16x32_bf16 v[62:65], v[170:173], v[154:157], v[62:65]
	ds_read_b128 v[214:217], v148 offset:36944
	ds_read_b128 v[198:201], v147 offset:80
	ds_read_b128 v[202:205], v147 offset:2384
	ds_read_b128 v[218:221], v148 offset:39248
	s_waitcnt lgkmcnt(7)
	v_mfma_f32_16x16x32_bf16 v[18:21], v[166:169], v[158:161], v[18:21]
	v_mfma_f32_16x16x32_bf16 v[26:29], v[170:173], v[158:161], v[26:29]
	s_waitcnt lgkmcnt(6)
	v_mfma_f32_16x16x32_bf16 v[22:25], v[166:169], v[162:165], v[22:25]
	v_mfma_f32_16x16x32_bf16 v[30:33], v[170:173], v[162:165], v[30:33]
	ds_read_b128 v[206:209], v147 offset:4688
	ds_read_b128 v[210:213], v147 offset:6992
	ds_read_b128 v[222:225], v148 offset:41552
	ds_read_b128 v[226:229], v148 offset:43856
	s_waitcnt lgkmcnt(9)
	v_mfma_f32_16x16x32_bf16 v[34:37], v[174:177], v[150:153], v[34:37]
	v_mfma_f32_16x16x32_bf16 v[38:41], v[174:177], v[154:157], v[38:41]
	v_mfma_f32_16x16x32_bf16 v[2:5], v[174:177], v[158:161], v[2:5]
	v_mfma_f32_16x16x32_bf16 v[6:9], v[174:177], v[162:165], v[6:9]
	s_waitcnt lgkmcnt(8)
	v_mfma_f32_16x16x32_bf16 v[42:45], v[178:181], v[150:153], v[42:45]
	v_mfma_f32_16x16x32_bf16 v[46:49], v[178:181], v[154:157], v[46:49]
	v_mfma_f32_16x16x32_bf16 v[10:13], v[178:181], v[158:161], v[10:13]
	v_mfma_f32_16x16x32_bf16 v[14:17], v[178:181], v[162:165], v[14:17]
	s_waitcnt lgkmcnt(6)
	v_mfma_f32_16x16x32_bf16 v[50:53], v[214:217], v[198:201], v[50:53]
	s_waitcnt lgkmcnt(5)
	v_mfma_f32_16x16x32_bf16 v[54:57], v[214:217], v[202:205], v[54:57]
	s_waitcnt vmcnt(6)
	ds_write_b128 v144, v[98:101] offset:18448
	ds_write_b128 v144, v[102:105] offset:55312
	s_waitcnt lgkmcnt(6)
	v_mfma_f32_16x16x32_bf16 v[58:61], v[218:221], v[198:201], v[58:61]
	v_mfma_f32_16x16x32_bf16 v[62:65], v[218:221], v[202:205], v[62:65]
	s_waitcnt lgkmcnt(5)
	v_mfma_f32_16x16x32_bf16 v[18:21], v[214:217], v[206:209], v[18:21]
	v_mfma_f32_16x16x32_bf16 v[26:29], v[218:221], v[206:209], v[26:29]
	s_waitcnt vmcnt(4)
	ds_write_b128 v144, v[106:109] offset:23056
	ds_write_b128 v144, v[110:113] offset:59920
	s_waitcnt lgkmcnt(6)
	v_mfma_f32_16x16x32_bf16 v[22:25], v[214:217], v[210:213], v[22:25]
	v_mfma_f32_16x16x32_bf16 v[30:33], v[218:221], v[210:213], v[30:33]
	s_waitcnt lgkmcnt(5)
	v_mfma_f32_16x16x32_bf16 v[34:37], v[222:225], v[198:201], v[34:37]
	v_mfma_f32_16x16x32_bf16 v[38:41], v[222:225], v[202:205], v[38:41]
	s_waitcnt vmcnt(2)
	ds_write_b128 v144, v[114:117] offset:27664
	ds_write_b128 v144, v[118:121] offset:64528
	v_mfma_f32_16x16x32_bf16 v[2:5], v[222:225], v[206:209], v[2:5]
	v_mfma_f32_16x16x32_bf16 v[6:9], v[222:225], v[210:213], v[6:9]
	s_waitcnt lgkmcnt(6)
	v_mfma_f32_16x16x32_bf16 v[42:45], v[226:229], v[198:201], v[42:45]
	v_mfma_f32_16x16x32_bf16 v[46:49], v[226:229], v[202:205], v[46:49]
	s_waitcnt vmcnt(0)
	ds_write_b128 v144, v[122:125] offset:32272
	ds_write_b128 v145, v[126:129] offset:32256
	v_mfma_f32_16x16x32_bf16 v[10:13], v[226:229], v[206:209], v[10:13]
	v_mfma_f32_16x16x32_bf16 v[14:17], v[226:229], v[210:213], v[14:17]
	s_waitcnt lgkmcnt(0)
	s_barrier
; template <bool SWAP, class Epi>
; DI void gemm_tile(const u16* __restrict__ A, int lda, const u16* __restrict__ Bt, int ldb, int K, int m0, int n0, char* smem, Epi&& epi) {
;     ...
;   auto compute = [&](int buf) __attribute__((always_inline)) {
;     bf16x8 af[2][2], bfr[2][2];
;     af[0][0] = *(const bf16x8*)(Asb + buf * 128 * 72);
;     af[0][1] = *(const bf16x8*)(Asb + buf * 128 * 72 + 32 * 72);
;     bfr[0][0] = *(const bf16x8*)(Bsb + buf * 128 * 72);
;     bfr[0][1] = *(const bf16x8*)(Bsb + buf * 128 * 72 + 32 * 72);
; #pragma unroll
;     for (int ks = 0; ks < 4; ++ks) {
;       const int c = ks & 1, n = c ^ 1;
;       if (ks < 3) {
;         af[n][0] = *(const bf16x8*)(Asb + buf * 128 * 72 + (ks + 1) * 16);
;         af[n][1] = *(const bf16x8*)(Asb + buf * 128 * 72 + 32 * 72 + (ks + 1) * 16);
;         bfr[n][0] = *(const bf16x8*)(Bsb + buf * 128 * 72 + (ks + 1) * 16);
;         bfr[n][1] = *(const bf16x8*)(Bsb + buf * 128 * 72 + 32 * 72 + (ks + 1) * 16);
;       }
;       __builtin_amdgcn_sched_barrier(0);
; #pragma unroll
;       for (int mi = 0; mi < 2; ++mi)
; #pragma unroll
;         for (int ni = 0; ni < 2; ++ni) {
;           if (SWAP) acc[mi][ni] = MFMA(bfr[c][ni], af[c][mi], acc[mi][ni]);
;           else acc[mi][ni] = MFMA(af[c][mi], bfr[c][ni], acc[mi][ni]);
;         }
;       __builtin_amdgcn_sched_barrier(0);
;     }
;   };
;   for (int kt = 0; kt < KT; kt += 2) {
;     if (kt + 2 < KT) {
;       const int k0 = (kt + 2) << 6;
; #pragma unroll
;       for (int i = 0; i < 4; ++i) { ra0[i] = *(const u32x4*)(ag + (size_t)i * 32 * lda + k0); rb0[i] = *(const u32x4*)(bg + (size_t)i * 32 * ldb + k0); }
;     }
;     compute(0);
; #pragma unroll
;     for (int i = 0; i < 4; ++i) { *(u32x4*)(asw + 128 * 72 + 32 * i * 72) = ra1[i]; *(u32x4*)(bsw + 128 * 72 + 32 * i * 72) = rb1[i]; }
;     __syncthreads();
;     if (kt + 3 < KT) {
;       const int k0 = (kt + 3) << 6;
; #pragma unroll
;       for (int i = 0; i < 4; ++i) { ra1[i] = *(const u32x4*)(ag + (size_t)i * 32 * lda + k0); rb1[i] = *(const u32x4*)(bg + (size_t)i * 32 * ldb + k0); }
;     }
;     compute(1);
;     if (kt + 2 < KT) {
; #pragma unroll
;       for (int i = 0; i < 4; ++i) { *(u32x4*)(asw + 32 * i * 72) = ra0[i]; *(u32x4*)(bsw + 32 * i * 72) = rb0[i]; }
;     }
;     __syncthreads();
;   }
;   epi(acc, m0 + wm * 64, n0 + wn * 64, r, hi);
	ds_read_b128 v[166:169], v148 offset:55312
	ds_read_b128 v[150:153], v147 offset:18448
	ds_read_b128 v[154:157], v147 offset:20752
	ds_read_b128 v[170:173], v148 offset:57616
	ds_read_b128 v[158:161], v147 offset:23056
	ds_read_b128 v[162:165], v147 offset:25360
	ds_read_b128 v[174:177], v148 offset:59920
	ds_read_b128 v[178:181], v148 offset:62224
	s_waitcnt lgkmcnt(6)
	v_mfma_f32_16x16x32_bf16 v[50:53], v[166:169], v[150:153], v[50:53]
	s_waitcnt lgkmcnt(5)
	v_mfma_f32_16x16x32_bf16 v[54:57], v[166:169], v[154:157], v[54:57]
	s_waitcnt lgkmcnt(4)
	v_mfma_f32_16x16x32_bf16 v[58:61], v[170:173], v[150:153], v[58:61]
	v_mfma_f32_16x16x32_bf16 v[62:65], v[170:173], v[154:157], v[62:65]
	ds_read_b128 v[214:217], v148 offset:55376
	ds_read_b128 v[198:201], v147 offset:18512
	ds_read_b128 v[202:205], v147 offset:20816
	ds_read_b128 v[218:221], v148 offset:57680
	s_waitcnt lgkmcnt(7)
	v_mfma_f32_16x16x32_bf16 v[18:21], v[166:169], v[158:161], v[18:21]
	v_mfma_f32_16x16x32_bf16 v[26:29], v[170:173], v[158:161], v[26:29]
	s_waitcnt lgkmcnt(6)
	v_mfma_f32_16x16x32_bf16 v[22:25], v[166:169], v[162:165], v[22:25]
	v_mfma_f32_16x16x32_bf16 v[30:33], v[170:173], v[162:165], v[30:33]
	ds_read_b128 v[206:209], v147 offset:23120
	ds_read_b128 v[210:213], v147 offset:25424
	ds_read_b128 v[222:225], v148 offset:59984
	ds_read_b128 v[226:229], v148 offset:62288
	s_waitcnt lgkmcnt(9)
	v_mfma_f32_16x16x32_bf16 v[34:37], v[174:177], v[150:153], v[34:37]
	v_mfma_f32_16x16x32_bf16 v[38:41], v[174:177], v[154:157], v[38:41]
	v_mfma_f32_16x16x32_bf16 v[2:5], v[174:177], v[158:161], v[2:5]
	v_mfma_f32_16x16x32_bf16 v[6:9], v[174:177], v[162:165], v[6:9]
	s_waitcnt lgkmcnt(8)
	v_mfma_f32_16x16x32_bf16 v[42:45], v[178:181], v[150:153], v[42:45]
	v_mfma_f32_16x16x32_bf16 v[46:49], v[178:181], v[154:157], v[46:49]
	v_mfma_f32_16x16x32_bf16 v[10:13], v[178:181], v[158:161], v[10:13]
	v_mfma_f32_16x16x32_bf16 v[14:17], v[178:181], v[162:165], v[14:17]
	s_waitcnt lgkmcnt(6)
	v_mfma_f32_16x16x32_bf16 v[50:53], v[214:217], v[198:201], v[50:53]
	s_waitcnt lgkmcnt(5)
	v_mfma_f32_16x16x32_bf16 v[54:57], v[214:217], v[202:205], v[54:57]
	s_waitcnt lgkmcnt(4)
	v_mfma_f32_16x16x32_bf16 v[58:61], v[218:221], v[198:201], v[58:61]
	v_mfma_f32_16x16x32_bf16 v[62:65], v[218:221], v[202:205], v[62:65]
	s_waitcnt lgkmcnt(3)
	v_mfma_f32_16x16x32_bf16 v[18:21], v[214:217], v[206:209], v[18:21]
	v_mfma_f32_16x16x32_bf16 v[26:29], v[218:221], v[206:209], v[26:29]
	s_waitcnt lgkmcnt(2)
	v_mfma_f32_16x16x32_bf16 v[22:25], v[214:217], v[210:213], v[22:25]
	v_mfma_f32_16x16x32_bf16 v[30:33], v[218:221], v[210:213], v[30:33]
	s_waitcnt lgkmcnt(1)
	v_mfma_f32_16x16x32_bf16 v[34:37], v[222:225], v[198:201], v[34:37]
	v_mfma_f32_16x16x32_bf16 v[38:41], v[222:225], v[202:205], v[38:41]
	v_mfma_f32_16x16x32_bf16 v[2:5], v[222:225], v[206:209], v[2:5]
	v_mfma_f32_16x16x32_bf16 v[6:9], v[222:225], v[210:213], v[6:9]
	s_waitcnt lgkmcnt(0)
	v_mfma_f32_16x16x32_bf16 v[42:45], v[226:229], v[198:201], v[42:45]
	v_mfma_f32_16x16x32_bf16 v[46:49], v[226:229], v[202:205], v[46:49]
	v_mfma_f32_16x16x32_bf16 v[10:13], v[226:229], v[206:209], v[10:13]
	v_mfma_f32_16x16x32_bf16 v[14:17], v[226:229], v[210:213], v[14:17]
	s_nop 7
	s_nop 7
	v_permlane16_swap_b32_e32 v50, v54
	v_permlane16_swap_b32_e32 v51, v55
	v_permlane16_swap_b32_e32 v52, v56
	v_permlane16_swap_b32_e32 v53, v57
	v_permlane16_swap_b32_e32 v58, v62
	v_permlane16_swap_b32_e32 v59, v63
	v_permlane16_swap_b32_e32 v60, v64
	v_permlane16_swap_b32_e32 v61, v65
	v_permlane16_swap_b32_e32 v34, v38
	v_permlane16_swap_b32_e32 v35, v39
	v_permlane16_swap_b32_e32 v36, v40
	v_permlane16_swap_b32_e32 v37, v41
	v_permlane16_swap_b32_e32 v42, v46
	v_permlane16_swap_b32_e32 v43, v47
	v_permlane16_swap_b32_e32 v44, v48
	v_permlane16_swap_b32_e32 v45, v49
	v_permlane16_swap_b32_e32 v18, v22
	v_permlane16_swap_b32_e32 v19, v23
	v_permlane16_swap_b32_e32 v20, v24
	v_permlane16_swap_b32_e32 v21, v25
	v_permlane16_swap_b32_e32 v26, v30
	v_permlane16_swap_b32_e32 v27, v31
	v_permlane16_swap_b32_e32 v28, v32
	v_permlane16_swap_b32_e32 v29, v33
	v_permlane16_swap_b32_e32 v2, v6
	v_permlane16_swap_b32_e32 v3, v7
	v_permlane16_swap_b32_e32 v4, v8
	v_permlane16_swap_b32_e32 v5, v9
	v_permlane16_swap_b32_e32 v10, v14
	v_permlane16_swap_b32_e32 v11, v15
	v_permlane16_swap_b32_e32 v12, v16
	v_permlane16_swap_b32_e32 v13, v17
	v_permlane32_swap_b32_e32 v50, v54
	v_permlane32_swap_b32_e32 v51, v55
	v_permlane32_swap_b32_e32 v52, v56
	v_permlane32_swap_b32_e32 v53, v57
	v_permlane32_swap_b32_e32 v58, v62
	v_permlane32_swap_b32_e32 v59, v63
	v_permlane32_swap_b32_e32 v60, v64
	v_permlane32_swap_b32_e32 v61, v65
	v_permlane32_swap_b32_e32 v34, v38
	v_permlane32_swap_b32_e32 v35, v39
	v_permlane32_swap_b32_e32 v36, v40
	v_permlane32_swap_b32_e32 v37, v41
	v_permlane32_swap_b32_e32 v42, v46
	v_permlane32_swap_b32_e32 v43, v47
	v_permlane32_swap_b32_e32 v44, v48
	v_permlane32_swap_b32_e32 v45, v49
	v_permlane32_swap_b32_e32 v18, v22
	v_permlane32_swap_b32_e32 v19, v23
	v_permlane32_swap_b32_e32 v20, v24
	v_permlane32_swap_b32_e32 v21, v25
	v_permlane32_swap_b32_e32 v26, v30
	v_permlane32_swap_b32_e32 v27, v31
	v_permlane32_swap_b32_e32 v28, v32
	v_permlane32_swap_b32_e32 v29, v33
	v_permlane32_swap_b32_e32 v2, v6
	v_permlane32_swap_b32_e32 v3, v7
	v_permlane32_swap_b32_e32 v4, v8
	v_permlane32_swap_b32_e32 v5, v9
	v_permlane32_swap_b32_e32 v10, v14
	v_permlane32_swap_b32_e32 v11, v15
	v_permlane32_swap_b32_e32 v12, v16
	v_permlane32_swap_b32_e32 v13, v17
	s_waitcnt lgkmcnt(0)
	s_barrier
	s_branch .LBB0_745

; template <bool SWAP, class Epi>
; DI void gemm_tile(const u16* __restrict__ A, int lda, const u16* __restrict__ Bt, int ldb, int K, int m0, int n0, char* smem, Epi&& epi) {
;     ...
;   const int tid = threadIdx.x, lane = tid & 63, w = tid >> 6, wm = w >> 1, wn = w & 1;
;   const int r = lane & 31, hi = lane >> 5;
;   f32x16 acc[2][2];
; #pragma unroll
;   for (int a = 0; a < 2; ++a)
; #pragma unroll
;     for (int b = 0; b < 2; ++b)
; #pragma unroll
;       for (int i = 0; i < 16; ++i) acc[a][b][i] = 0.f;
;   const int srow = tid >> 3, skc = tid & 7;
;   const u16* ag = A + (size_t)(m0 + srow) * lda + skc * 8;
;   const u16* bg = Bt + (size_t)(n0 + srow) * ldb + skc * 8;
;   u16* asw = As + srow * 72 + skc * 8;
;   u16* bsw = Bs + srow * 72 + skc * 8;
;   u32x4 ra0[4], rb0[4], ra1[4], rb1[4];
; #pragma unroll
;   for (int i = 0; i < 4; ++i) { ra0[i] = *(const u32x4*)(ag + (size_t)i * 32 * lda); rb0[i] = *(const u32x4*)(bg + (size_t)i * 32 * ldb); }
; #pragma unroll
;   for (int i = 0; i < 4; ++i) { ra1[i] = *(const u32x4*)(ag + (size_t)i * 32 * lda + 64); rb1[i] = *(const u32x4*)(bg + (size_t)i * 32 * ldb + 64); }
;   __syncthreads();
; #pragma unroll
;   for (int i = 0; i < 4; ++i) { *(u32x4*)(asw + 32 * i * 72) = ra0[i]; *(u32x4*)(bsw + 32 * i * 72) = rb0[i]; }
;   __syncthreads();
;   const int KT = K >> 6;
;   const u16* Asb = As + (wm * 64 + r) * 72 + hi * 8;
;   const u16* Bsb = Bs + (wn * 64 + r) * 72 + hi * 8;
; DI void phase7(const Params& p, char* smem) {
;     ...
;   for (int it = blockIdx.x; it < 64 * 16; it += gridDim.x) {
;     const int tn = it / 64, tm = it % 64;
;     gemm_tile<true>(H2, D_, W, D_, D_, tm * 128, tn * 128, smem, [&](f32x16 (&acc)[2][2], int mb, int nb, int r, int hi) __attribute__((always_inline)) {
.Lprio_p7:
	s_waitcnt lgkmcnt(0)
	v_lshlrev_b32_e32 v2, 4, v0
	v_and_b32_e32 v130, 0x70, v2
	v_mov_b32_e32 v131, 0
	v_lshl_add_u64 v[2:3], s[82:83], 0, v[130:131]
	s_mov_b64 s[4:5], 0x6538000
	v_lshrrev_b32_e32 v1, 3, v0
	s_waitcnt vmcnt(9)
	v_lshl_add_u64 v[132:133], v[2:3], 0, s[4:5]
	s_mov_b64 s[4:5], 0x1cb8000
	v_lshl_add_u64 v[134:135], v[2:3], 0, s[4:5]
	v_mul_u32_u24_e32 v2, 0x48, v1
	v_and_b32_e32 v4, 31, v0
	v_lshlrev_b32_e32 v2, 1, v2
	v_lshrrev_b32_e32 v3, 1, v0
	s_waitcnt vmcnt(6)
	v_add3_u32 v144, 0, v2, v130
	v_bfe_u32 v2, v0, 5, 1
	v_and_or_b32 v146, v3, 64, v4
	v_mul_u32_u24_e32 v3, 0x90, v146
	v_lshlrev_b32_e32 v4, 4, v2
	v_add3_u32 v147, 0, v3, v4
	v_and_b32_e32 v3, 0x5f, v0
	s_load_dword s10, s[0:1], 0xc0
	v_mul_u32_u24_e32 v3, 0x90, v3
	s_waitcnt vmcnt(5)
	v_add3_u32 v148, 0, v3, v4
	v_and_b32_e32 v3, 64, v0
	s_add_u32 s2, s82, 0x8538000
	v_lshl_or_b32 v149, v2, 2, v3
	v_and_b32_e32 v2, 7, v0
	s_addc_u32 s3, s83, 0
	v_add_u32_e32 v145, 0x9010, v144
	v_lshlrev_b32_e32 v130, 4, v2
	s_mov_b32 s11, 0x20000
	s_mov_b32 s13, 0x40000
	s_mov_b32 s14, 0x60000
	s_mov_b64 s[4:5], 0x100
	s_mov_b32 s15, s12
	v_lshrrev_b32_e32 v198, 3, v0
	v_lshrrev_b32_e32 v199, 2, v198
	v_lshrrev_b32_e32 v200, 3, v198
	v_xor_b32_e32 v199, v199, v200
	v_and_b32_e32 v199, 1, v199
	v_and_b32_e32 v200, 1, v0
	v_lshlrev_b32_e32 v200, 5, v200
	v_sub_u32_e32 v200, 16, v200
	v_mul_lo_u32 v199, v199, v200
	v_add_u32_e32 v144, v144, v199
	v_add_u32_e32 v145, v145, v199
	v_and_b32_e32 v198, 15, v0
	v_bfe_u32 v199, v0, 4, 2
	v_lshrrev_b32_e32 v200, 2, v198
	v_lshrrev_b32_e32 v201, 3, v198
	v_xor_b32_e32 v200, v200, v201
	v_and_b32_e32 v200, 1, v200
	v_xor_b32_e32 v199, v199, v200
	v_lshlrev_b32_e32 v199, 4, v199
	v_bfe_u32 v200, v0, 7, 1
	v_lshl_or_b32 v200, v200, 6, v198
	v_mul_u32_u24_e32 v200, 0x90, v200
	v_add_u32_e32 v147, v200, v199
	v_bfe_u32 v200, v0, 6, 1
	v_lshl_or_b32 v200, v200, 6, v198
	v_mul_u32_u24_e32 v200, 0x90, v200
	v_add_u32_e32 v148, v200, v199
	s_branch .LBB0_953

; #define MFMA(a, b, c) __builtin_amdgcn_mfma_f32_32x32x16_bf16((a), (b), (c), 0, 0, 0)
; template <bool SWAP, class Epi>
; DI void gemm_tile(const u16* __restrict__ A, int lda, const u16* __restrict__ Bt, int ldb, int K, int m0, int n0, char* smem, Epi&& epi) {
;     ...
;   auto compute = [&](int buf) __attribute__((always_inline)) {
;     bf16x8 af[2][2], bfr[2][2];
;     af[0][0] = *(const bf16x8*)(Asb + buf * 128 * 72);
;     af[0][1] = *(const bf16x8*)(Asb + buf * 128 * 72 + 32 * 72);
;     bfr[0][0] = *(const bf16x8*)(Bsb + buf * 128 * 72);
;     bfr[0][1] = *(const bf16x8*)(Bsb + buf * 128 * 72 + 32 * 72);
; #pragma unroll
;     for (int ks = 0; ks < 4; ++ks) {
;       const int c = ks & 1, n = c ^ 1;
;       if (ks < 3) {
;         af[n][0] = *(const bf16x8*)(Asb + buf * 128 * 72 + (ks + 1) * 16);
;         af[n][1] = *(const bf16x8*)(Asb + buf * 128 * 72 + 32 * 72 + (ks + 1) * 16);
;         bfr[n][0] = *(const bf16x8*)(Bsb + buf * 128 * 72 + (ks + 1) * 16);
;         bfr[n][1] = *(const bf16x8*)(Bsb + buf * 128 * 72 + 32 * 72 + (ks + 1) * 16);
;       }
;       __builtin_amdgcn_sched_barrier(0);
; #pragma unroll
;       for (int mi = 0; mi < 2; ++mi)
; #pragma unroll
;         for (int ni = 0; ni < 2; ++ni) {
;           if (SWAP) acc[mi][ni] = MFMA(bfr[c][ni], af[c][mi], acc[mi][ni]);
;           else acc[mi][ni] = MFMA(af[c][mi], bfr[c][ni], acc[mi][ni]);
;         }
;       __builtin_amdgcn_sched_barrier(0);
;     }
;   };
;   for (int kt = 0; kt < KT; kt += 2) {
;     if (kt + 2 < KT) {
;       const int k0 = (kt + 2) << 6;
; #pragma unroll
;       for (int i = 0; i < 4; ++i) { ra0[i] = *(const u32x4*)(ag + (size_t)i * 32 * lda + k0); rb0[i] = *(const u32x4*)(bg + (size_t)i * 32 * ldb + k0); }
;     }
;     compute(0);
; #pragma unroll
;     for (int i = 0; i < 4; ++i) { *(u32x4*)(asw + 128 * 72 + 32 * i * 72) = ra1[i]; *(u32x4*)(bsw + 128 * 72 + 32 * i * 72) = rb1[i]; }
;     __syncthreads();
;     if (kt + 3 < KT) {
;       const int k0 = (kt + 3) << 6;
; #pragma unroll
;       for (int i = 0; i < 4; ++i) { ra1[i] = *(const u32x4*)(ag + (size_t)i * 32 * lda + k0); rb1[i] = *(const u32x4*)(bg + (size_t)i * 32 * ldb + k0); }
;     }
;     compute(1);
;     if (kt + 2 < KT) {
; #pragma unroll
;       for (int i = 0; i < 4; ++i) { *(u32x4*)(asw + 32 * i * 72) = ra0[i]; *(u32x4*)(bsw + 32 * i * 72) = rb0[i]; }
;     }
;     __syncthreads();
;   }
.LBB0_955:
	global_load_dwordx4 v[66:69], v194, s[100:101] offset:256
	global_load_dwordx4 v[70:73], v190, s[98:99] offset:256
	global_load_dwordx4 v[74:77], v195, s[100:101] offset:256
	global_load_dwordx4 v[78:81], v191, s[98:99] offset:256
	global_load_dwordx4 v[82:85], v196, s[100:101] offset:256
	global_load_dwordx4 v[86:89], v192, s[98:99] offset:256
	global_load_dwordx4 v[90:93], v197, s[100:101] offset:256
	global_load_dwordx4 v[94:97], v193, s[98:99] offset:256
	ds_read_b128 v[166:169], v148 offset:36880
	ds_read_b128 v[150:153], v147 offset:16
	ds_read_b128 v[154:157], v147 offset:2320
	ds_read_b128 v[170:173], v148 offset:39184
	ds_read_b128 v[158:161], v147 offset:4624
	ds_read_b128 v[162:165], v147 offset:6928
	ds_read_b128 v[174:177], v148 offset:41488
	ds_read_b128 v[178:181], v148 offset:43792
	s_waitcnt lgkmcnt(6)
	v_mfma_f32_16x16x32_bf16 v[50:53], v[166:169], v[150:153], v[50:53]
	s_waitcnt lgkmcnt(5)
	v_mfma_f32_16x16x32_bf16 v[54:57], v[166:169], v[154:157], v[54:57]
	s_waitcnt lgkmcnt(4)
	v_mfma_f32_16x16x32_bf16 v[58:61], v[170:173], v[150:153], v[58:61]
	v_mfma_f32_16x16x32_bf16 v[62:65], v[170:173], v[154:157], v[62:65]
	ds_read_b128 v[214:217], v148 offset:36944
	ds_read_b128 v[198:201], v147 offset:80
	ds_read_b128 v[202:205], v147 offset:2384
	ds_read_b128 v[218:221], v148 offset:39248
	s_waitcnt lgkmcnt(7)
	v_mfma_f32_16x16x32_bf16 v[18:21], v[166:169], v[158:161], v[18:21]
	v_mfma_f32_16x16x32_bf16 v[26:29], v[170:173], v[158:161], v[26:29]
	s_waitcnt lgkmcnt(6)
	v_mfma_f32_16x16x32_bf16 v[22:25], v[166:169], v[162:165], v[22:25]
	v_mfma_f32_16x16x32_bf16 v[30:33], v[170:173], v[162:165], v[30:33]
	ds_read_b128 v[206:209], v147 offset:4688
	ds_read_b128 v[210:213], v147 offset:6992
	ds_read_b128 v[222:225], v148 offset:41552
	ds_read_b128 v[226:229], v148 offset:43856
	s_waitcnt lgkmcnt(9)
	v_mfma_f32_16x16x32_bf16 v[34:37], v[174:177], v[150:153], v[34:37]
	v_mfma_f32_16x16x32_bf16 v[38:41], v[174:177], v[154:157], v[38:41]
	v_mfma_f32_16x16x32_bf16 v[2:5], v[174:177], v[158:161], v[2:5]
	v_mfma_f32_16x16x32_bf16 v[6:9], v[174:177], v[162:165], v[6:9]
	s_waitcnt lgkmcnt(8)
	v_mfma_f32_16x16x32_bf16 v[42:45], v[178:181], v[150:153], v[42:45]
	v_mfma_f32_16x16x32_bf16 v[46:49], v[178:181], v[154:157], v[46:49]
	v_mfma_f32_16x16x32_bf16 v[10:13], v[178:181], v[158:161], v[10:13]
	v_mfma_f32_16x16x32_bf16 v[14:17], v[178:181], v[162:165], v[14:17]
	s_waitcnt lgkmcnt(6)
	v_mfma_f32_16x16x32_bf16 v[50:53], v[214:217], v[198:201], v[50:53]
	s_waitcnt lgkmcnt(5)
	v_mfma_f32_16x16x32_bf16 v[54:57], v[214:217], v[202:205], v[54:57]
	s_waitcnt vmcnt(14)
	ds_write_b128 v144, v[98:101] offset:18448
	ds_write_b128 v144, v[102:105] offset:55312
	s_waitcnt lgkmcnt(6)
	v_mfma_f32_16x16x32_bf16 v[58:61], v[218:221], v[198:201], v[58:61]
	v_mfma_f32_16x16x32_bf16 v[62:65], v[218:221], v[202:205], v[62:65]
	s_waitcnt lgkmcnt(5)
	v_mfma_f32_16x16x32_bf16 v[18:21], v[214:217], v[206:209], v[18:21]
	v_mfma_f32_16x16x32_bf16 v[26:29], v[218:221], v[206:209], v[26:29]
	s_waitcnt vmcnt(12)
	ds_write_b128 v144, v[106:109] offset:23056
	ds_write_b128 v144, v[110:113] offset:59920
	s_waitcnt lgkmcnt(6)
	v_mfma_f32_16x16x32_bf16 v[22:25], v[214:217], v[210:213], v[22:25]
	v_mfma_f32_16x16x32_bf16 v[30:33], v[218:221], v[210:213], v[30:33]
	s_waitcnt lgkmcnt(5)
	v_mfma_f32_16x16x32_bf16 v[34:37], v[222:225], v[198:201], v[34:37]
	v_mfma_f32_16x16x32_bf16 v[38:41], v[222:225], v[202:205], v[38:41]
	s_waitcnt vmcnt(10)
	ds_write_b128 v144, v[114:117] offset:27664
	ds_write_b128 v144, v[118:121] offset:64528
	v_mfma_f32_16x16x32_bf16 v[2:5], v[222:225], v[206:209], v[2:5]
	v_mfma_f32_16x16x32_bf16 v[6:9], v[222:225], v[210:213], v[6:9]
	s_waitcnt lgkmcnt(6)
	v_mfma_f32_16x16x32_bf16 v[42:45], v[226:229], v[198:201], v[42:45]
	v_mfma_f32_16x16x32_bf16 v[46:49], v[226:229], v[202:205], v[46:49]
	s_waitcnt vmcnt(8)
	ds_write_b128 v144, v[122:125] offset:32272
	ds_write_b128 v145, v[126:129] offset:32256
	v_mfma_f32_16x16x32_bf16 v[10:13], v[226:229], v[206:209], v[10:13]
	v_mfma_f32_16x16x32_bf16 v[14:17], v[226:229], v[210:213], v[14:17]
	s_waitcnt lgkmcnt(0)
	s_barrier
	global_load_dwordx4 v[98:101], v194, s[100:101] offset:384
	global_load_dwordx4 v[102:105], v190, s[98:99] offset:384
	global_load_dwordx4 v[106:109], v195, s[100:101] offset:384
	global_load_dwordx4 v[110:113], v191, s[98:99] offset:384
	global_load_dwordx4 v[114:117], v196, s[100:101] offset:384
	global_load_dwordx4 v[118:121], v192, s[98:99] offset:384
	global_load_dwordx4 v[122:125], v197, s[100:101] offset:384
	global_load_dwordx4 v[126:129], v193, s[98:99] offset:384
	ds_read_b128 v[166:169], v148 offset:55312
	ds_read_b128 v[150:153], v147 offset:18448
	ds_read_b128 v[154:157], v147 offset:20752
	ds_read_b128 v[170:173], v148 offset:57616
	ds_read_b128 v[158:161], v147 offset:23056
	ds_read_b128 v[162:165], v147 offset:25360
	ds_read_b128 v[174:177], v148 offset:59920
	ds_read_b128 v[178:181], v148 offset:62224
	s_waitcnt lgkmcnt(6)
	v_mfma_f32_16x16x32_bf16 v[50:53], v[166:169], v[150:153], v[50:53]
	s_waitcnt lgkmcnt(5)
	v_mfma_f32_16x16x32_bf16 v[54:57], v[166:169], v[154:157], v[54:57]
	s_waitcnt lgkmcnt(4)
	v_mfma_f32_16x16x32_bf16 v[58:61], v[170:173], v[150:153], v[58:61]
	v_mfma_f32_16x16x32_bf16 v[62:65], v[170:173], v[154:157], v[62:65]
	ds_read_b128 v[214:217], v148 offset:55376
	ds_read_b128 v[198:201], v147 offset:18512
	ds_read_b128 v[202:205], v147 offset:20816
	ds_read_b128 v[218:221], v148 offset:57680
	s_waitcnt lgkmcnt(7)
	v_mfma_f32_16x16x32_bf16 v[18:21], v[166:169], v[158:161], v[18:21]
	v_mfma_f32_16x16x32_bf16 v[26:29], v[170:173], v[158:161], v[26:29]
	s_waitcnt lgkmcnt(6)
; #define MFMA(a, b, c) __builtin_amdgcn_mfma_f32_32x32x16_bf16((a), (b), (c), 0, 0, 0)
; template <bool SWAP, class Epi>
; DI void gemm_tile(const u16* __restrict__ A, int lda, const u16* __restrict__ Bt, int ldb, int K, int m0, int n0, char* smem, Epi&& epi) {
;     ...
;   auto compute = [&](int buf) __attribute__((always_inline)) {
;     bf16x8 af[2][2], bfr[2][2];
;     af[0][0] = *(const bf16x8*)(Asb + buf * 128 * 72);
;     af[0][1] = *(const bf16x8*)(Asb + buf * 128 * 72 + 32 * 72);
;     bfr[0][0] = *(const bf16x8*)(Bsb + buf * 128 * 72);
;     bfr[0][1] = *(const bf16x8*)(Bsb + buf * 128 * 72 + 32 * 72);
; #pragma unroll
;     for (int ks = 0; ks < 4; ++ks) {
;       const int c = ks & 1, n = c ^ 1;
;       if (ks < 3) {
;         af[n][0] = *(const bf16x8*)(Asb + buf * 128 * 72 + (ks + 1) * 16);
;         af[n][1] = *(const bf16x8*)(Asb + buf * 128 * 72 + 32 * 72 + (ks + 1) * 16);
;         bfr[n][0] = *(const bf16x8*)(Bsb + buf * 128 * 72 + (ks + 1) * 16);
;         bfr[n][1] = *(const bf16x8*)(Bsb + buf * 128 * 72 + 32 * 72 + (ks + 1) * 16);
;       }
;       __builtin_amdgcn_sched_barrier(0);
; #pragma unroll
;       for (int mi = 0; mi < 2; ++mi)
; #pragma unroll
;         for (int ni = 0; ni < 2; ++ni) {
;           if (SWAP) acc[mi][ni] = MFMA(bfr[c][ni], af[c][mi], acc[mi][ni]);
;           else acc[mi][ni] = MFMA(af[c][mi], bfr[c][ni], acc[mi][ni]);
;         }
;       __builtin_amdgcn_sched_barrier(0);
;     }
;   };
;   for (int kt = 0; kt < KT; kt += 2) {
;     if (kt + 2 < KT) {
;       const int k0 = (kt + 2) << 6;
; #pragma unroll
;       for (int i = 0; i < 4; ++i) { ra0[i] = *(const u32x4*)(ag + (size_t)i * 32 * lda + k0); rb0[i] = *(const u32x4*)(bg + (size_t)i * 32 * ldb + k0); }
;     }
;     compute(0);
; #pragma unroll
;     for (int i = 0; i < 4; ++i) { *(u32x4*)(asw + 128 * 72 + 32 * i * 72) = ra1[i]; *(u32x4*)(bsw + 128 * 72 + 32 * i * 72) = rb1[i]; }
;     __syncthreads();
;     if (kt + 3 < KT) {
;       const int k0 = (kt + 3) << 6;
; #pragma unroll
;       for (int i = 0; i < 4; ++i) { ra1[i] = *(const u32x4*)(ag + (size_t)i * 32 * lda + k0); rb1[i] = *(const u32x4*)(bg + (size_t)i * 32 * ldb + k0); }
;     }
;     compute(1);
;     if (kt + 2 < KT) {
; #pragma unroll
;       for (int i = 0; i < 4; ++i) { *(u32x4*)(asw + 32 * i * 72) = ra0[i]; *(u32x4*)(bsw + 32 * i * 72) = rb0[i]; }
;     }
;     __syncthreads();
;   }
	v_mfma_f32_16x16x32_bf16 v[22:25], v[166:169], v[162:165], v[22:25]
	v_mfma_f32_16x16x32_bf16 v[30:33], v[170:173], v[162:165], v[30:33]
	ds_read_b128 v[206:209], v147 offset:23120
	ds_read_b128 v[210:213], v147 offset:25424
	ds_read_b128 v[222:225], v148 offset:59984
	ds_read_b128 v[226:229], v148 offset:62288
	s_waitcnt lgkmcnt(9)
	v_mfma_f32_16x16x32_bf16 v[34:37], v[174:177], v[150:153], v[34:37]
	v_mfma_f32_16x16x32_bf16 v[38:41], v[174:177], v[154:157], v[38:41]
	v_mfma_f32_16x16x32_bf16 v[2:5], v[174:177], v[158:161], v[2:5]
	v_mfma_f32_16x16x32_bf16 v[6:9], v[174:177], v[162:165], v[6:9]
	s_waitcnt lgkmcnt(8)
	v_mfma_f32_16x16x32_bf16 v[42:45], v[178:181], v[150:153], v[42:45]
	v_mfma_f32_16x16x32_bf16 v[46:49], v[178:181], v[154:157], v[46:49]
	v_mfma_f32_16x16x32_bf16 v[10:13], v[178:181], v[158:161], v[10:13]
	v_mfma_f32_16x16x32_bf16 v[14:17], v[178:181], v[162:165], v[14:17]
	s_waitcnt lgkmcnt(6)
	v_mfma_f32_16x16x32_bf16 v[50:53], v[214:217], v[198:201], v[50:53]
	s_waitcnt lgkmcnt(5)
	v_mfma_f32_16x16x32_bf16 v[54:57], v[214:217], v[202:205], v[54:57]
	s_waitcnt vmcnt(14)
	ds_write_b128 v144, v[66:69] offset:16
	ds_write_b128 v144, v[70:73] offset:36880
	s_waitcnt lgkmcnt(6)
	v_mfma_f32_16x16x32_bf16 v[58:61], v[218:221], v[198:201], v[58:61]
	v_mfma_f32_16x16x32_bf16 v[62:65], v[218:221], v[202:205], v[62:65]
	s_waitcnt lgkmcnt(5)
	v_mfma_f32_16x16x32_bf16 v[18:21], v[214:217], v[206:209], v[18:21]
	v_mfma_f32_16x16x32_bf16 v[26:29], v[218:221], v[206:209], v[26:29]
	s_waitcnt vmcnt(12)
	ds_write_b128 v144, v[74:77] offset:4624
	ds_write_b128 v144, v[78:81] offset:41488
	s_waitcnt lgkmcnt(6)
	v_mfma_f32_16x16x32_bf16 v[22:25], v[214:217], v[210:213], v[22:25]
	v_mfma_f32_16x16x32_bf16 v[30:33], v[218:221], v[210:213], v[30:33]
	s_waitcnt lgkmcnt(5)
	v_mfma_f32_16x16x32_bf16 v[34:37], v[222:225], v[198:201], v[34:37]
	v_mfma_f32_16x16x32_bf16 v[38:41], v[222:225], v[202:205], v[38:41]
	s_waitcnt vmcnt(10)
	ds_write_b128 v144, v[82:85] offset:9232
	ds_write_b128 v144, v[86:89] offset:46096
	v_mfma_f32_16x16x32_bf16 v[2:5], v[222:225], v[206:209], v[2:5]
	v_mfma_f32_16x16x32_bf16 v[6:9], v[222:225], v[210:213], v[6:9]
	s_waitcnt lgkmcnt(6)
	v_mfma_f32_16x16x32_bf16 v[42:45], v[226:229], v[198:201], v[42:45]
	v_mfma_f32_16x16x32_bf16 v[46:49], v[226:229], v[202:205], v[46:49]
	s_waitcnt vmcnt(8)
	ds_write_b128 v144, v[90:93] offset:13840
	ds_write_b128 v144, v[94:97] offset:50704
	v_mfma_f32_16x16x32_bf16 v[10:13], v[226:229], v[206:209], v[10:13]
	v_mfma_f32_16x16x32_bf16 v[14:17], v[226:229], v[210:213], v[14:17]
	s_add_i32 s18, s18, 2
	s_add_u32 s98, s98, 256
	s_addc_u32 s99, s99, 0
	s_add_u32 s100, s100, 256
	s_addc_u32 s101, s101, 0
	s_waitcnt lgkmcnt(0)
	s_barrier
	s_cmp_lt_u32 s18, 30
	s_cbranch_scc1 .LBB0_955
	ds_read_b128 v[166:169], v148 offset:36880
	ds_read_b128 v[150:153], v147 offset:16
	ds_read_b128 v[154:157], v147 offset:2320
	ds_read_b128 v[170:173], v148 offset:39184
	ds_read_b128 v[158:161], v147 offset:4624
	ds_read_b128 v[162:165], v147 offset:6928
	ds_read_b128 v[174:177], v148 offset:41488
	ds_read_b128 v[178:181], v148 offset:43792
	s_waitcnt lgkmcnt(6)
	v_mfma_f32_16x16x32_bf16 v[50:53], v[166:169], v[150:153], v[50:53]
	s_waitcnt lgkmcnt(5)
	v_mfma_f32_16x16x32_bf16 v[54:57], v[166:169], v[154:157], v[54:57]
	s_waitcnt lgkmcnt(4)
	v_mfma_f32_16x16x32_bf16 v[58:61], v[170:173], v[150:153], v[58:61]
	v_mfma_f32_16x16x32_bf16 v[62:65], v[170:173], v[154:157], v[62:65]
	ds_read_b128 v[214:217], v148 offset:36944
	ds_read_b128 v[198:201], v147 offset:80
	ds_read_b128 v[202:205], v147 offset:2384
	ds_read_b128 v[218:221], v148 offset:39248
	s_waitcnt lgkmcnt(7)
	v_mfma_f32_16x16x32_bf16 v[18:21], v[166:169], v[158:161], v[18:21]
	v_mfma_f32_16x16x32_bf16 v[26:29], v[170:173], v[158:161], v[26:29]
	s_waitcnt lgkmcnt(6)
	v_mfma_f32_16x16x32_bf16 v[22:25], v[166:169], v[162:165], v[22:25]
	v_mfma_f32_16x16x32_bf16 v[30:33], v[170:173], v[162:165], v[30:33]
	ds_read_b128 v[206:209], v147 offset:4688
	ds_read_b128 v[210:213], v147 offset:6992
	ds_read_b128 v[222:225], v148 offset:41552
	ds_read_b128 v[226:229], v148 offset:43856
	s_waitcnt lgkmcnt(9)
	v_mfma_f32_16x16x32_bf16 v[34:37], v[174:177], v[150:153], v[34:37]
	v_mfma_f32_16x16x32_bf16 v[38:41], v[174:177], v[154:157], v[38:41]
	v_mfma_f32_16x16x32_bf16 v[2:5], v[174:177], v[158:161], v[2:5]
	v_mfma_f32_16x16x32_bf16 v[6:9], v[174:177], v[162:165], v[6:9]
	s_waitcnt lgkmcnt(8)
	v_mfma_f32_16x16x32_bf16 v[42:45], v[178:181], v[150:153], v[42:45]
	v_mfma_f32_16x16x32_bf16 v[46:49], v[178:181], v[154:157], v[46:49]
	v_mfma_f32_16x16x32_bf16 v[10:13], v[178:181], v[158:161], v[10:13]
	v_mfma_f32_16x16x32_bf16 v[14:17], v[178:181], v[162:165], v[14:17]
	s_waitcnt lgkmcnt(6)
	v_mfma_f32_16x16x32_bf16 v[50:53], v[214:217], v[198:201], v[50:53]
	s_waitcnt lgkmcnt(5)
	v_mfma_f32_16x16x32_bf16 v[54:57], v[214:217], v[202:205], v[54:57]
	s_waitcnt vmcnt(6)
	ds_write_b128 v144, v[98:101] offset:18448
	ds_write_b128 v144, v[102:105] offset:55312
	s_waitcnt lgkmcnt(6)
	v_mfma_f32_16x16x32_bf16 v[58:61], v[218:221], v[198:201], v[58:61]
	v_mfma_f32_16x16x32_bf16 v[62:65], v[218:221], v[202:205], v[62:65]
	s_waitcnt lgkmcnt(5)
	v_mfma_f32_16x16x32_bf16 v[18:21], v[214:217], v[206:209], v[18:21]
	v_mfma_f32_16x16x32_bf16 v[26:29], v[218:221], v[206:209], v[26:29]
	s_waitcnt vmcnt(4)
	ds_write_b128 v144, v[106:109] offset:23056
	ds_write_b128 v144, v[110:113] offset:59920
	s_waitcnt lgkmcnt(6)
	v_mfma_f32_16x16x32_bf16 v[22:25], v[214:217], v[210:213], v[22:25]
	v_mfma_f32_16x16x32_bf16 v[30:33], v[218:221], v[210:213], v[30:33]
	s_waitcnt lgkmcnt(5)
	v_mfma_f32_16x16x32_bf16 v[34:37], v[222:225], v[198:201], v[34:37]
	v_mfma_f32_16x16x32_bf16 v[38:41], v[222:225], v[202:205], v[38:41]
	s_waitcnt vmcnt(2)
	ds_write_b128 v144, v[114:117] offset:27664
	ds_write_b128 v144, v[118:121] offset:64528
	v_mfma_f32_16x16x32_bf16 v[2:5], v[222:225], v[206:209], v[2:5]
	v_mfma_f32_16x16x32_bf16 v[6:9], v[222:225], v[210:213], v[6:9]
	s_waitcnt lgkmcnt(6)
	v_mfma_f32_16x16x32_bf16 v[42:45], v[226:229], v[198:201], v[42:45]
	v_mfma_f32_16x16x32_bf16 v[46:49], v[226:229], v[202:205], v[46:49]
	s_waitcnt vmcnt(0)
	ds_write_b128 v144, v[122:125] offset:32272
	ds_write_b128 v145, v[126:129] offset:32256
	v_mfma_f32_16x16x32_bf16 v[10:13], v[226:229], v[206:209], v[10:13]
	v_mfma_f32_16x16x32_bf16 v[14:17], v[226:229], v[210:213], v[14:17]
	s_waitcnt lgkmcnt(0)
	s_barrier
; template <bool SWAP, class Epi>
; DI void gemm_tile(const u16* __restrict__ A, int lda, const u16* __restrict__ Bt, int ldb, int K, int m0, int n0, char* smem, Epi&& epi) {
;     ...
;   auto compute = [&](int buf) __attribute__((always_inline)) {
;     bf16x8 af[2][2], bfr[2][2];
;     af[0][0] = *(const bf16x8*)(Asb + buf * 128 * 72);
;     af[0][1] = *(const bf16x8*)(Asb + buf * 128 * 72 + 32 * 72);
;     bfr[0][0] = *(const bf16x8*)(Bsb + buf * 128 * 72);
;     bfr[0][1] = *(const bf16x8*)(Bsb + buf * 128 * 72 + 32 * 72);
; #pragma unroll
;     for (int ks = 0; ks < 4; ++ks) {
;       const int c = ks & 1, n = c ^ 1;
;       if (ks < 3) {
;         af[n][0] = *(const bf16x8*)(Asb + buf * 128 * 72 + (ks + 1) * 16);
;         af[n][1] = *(const bf16x8*)(Asb + buf * 128 * 72 + 32 * 72 + (ks + 1) * 16);
;         bfr[n][0] = *(const bf16x8*)(Bsb + buf * 128 * 72 + (ks + 1) * 16);
;         bfr[n][1] = *(const bf16x8*)(Bsb + buf * 128 * 72 + 32 * 72 + (ks + 1) * 16);
;       }
;       __builtin_amdgcn_sched_barrier(0);
; #pragma unroll
;       for (int mi = 0; mi < 2; ++mi)
; #pragma unroll
;         for (int ni = 0; ni < 2; ++ni) {
;           if (SWAP) acc[mi][ni] = MFMA(bfr[c][ni], af[c][mi], acc[mi][ni]);
;           else acc[mi][ni] = MFMA(af[c][mi], bfr[c][ni], acc[mi][ni]);
;         }
;       __builtin_amdgcn_sched_barrier(0);
;     }
;   };
;   for (int kt = 0; kt < KT; kt += 2) {
;     if (kt + 2 < KT) {
;       const int k0 = (kt + 2) << 6;
; #pragma unroll
;       for (int i = 0; i < 4; ++i) { ra0[i] = *(const u32x4*)(ag + (size_t)i * 32 * lda + k0); rb0[i] = *(const u32x4*)(bg + (size_t)i * 32 * ldb + k0); }
;     }
;     compute(0);
; #pragma unroll
;     for (int i = 0; i < 4; ++i) { *(u32x4*)(asw + 128 * 72 + 32 * i * 72) = ra1[i]; *(u32x4*)(bsw + 128 * 72 + 32 * i * 72) = rb1[i]; }
;     __syncthreads();
;     if (kt + 3 < KT) {
;       const int k0 = (kt + 3) << 6;
; #pragma unroll
;       for (int i = 0; i < 4; ++i) { ra1[i] = *(const u32x4*)(ag + (size_t)i * 32 * lda + k0); rb1[i] = *(const u32x4*)(bg + (size_t)i * 32 * ldb + k0); }
;     }
;     compute(1);
;     if (kt + 2 < KT) {
; #pragma unroll
;       for (int i = 0; i < 4; ++i) { *(u32x4*)(asw + 32 * i * 72) = ra0[i]; *(u32x4*)(bsw + 32 * i * 72) = rb0[i]; }
;     }
;     __syncthreads();
;   }
;   epi(acc, m0 + wm * 64, n0 + wn * 64, r, hi);
	ds_read_b128 v[166:169], v148 offset:55312
	ds_read_b128 v[150:153], v147 offset:18448
	ds_read_b128 v[154:157], v147 offset:20752
	ds_read_b128 v[170:173], v148 offset:57616
	ds_read_b128 v[158:161], v147 offset:23056
	ds_read_b128 v[162:165], v147 offset:25360
	ds_read_b128 v[174:177], v148 offset:59920
	ds_read_b128 v[178:181], v148 offset:62224
	s_waitcnt lgkmcnt(6)
	v_mfma_f32_16x16x32_bf16 v[50:53], v[166:169], v[150:153], v[50:53]
	s_waitcnt lgkmcnt(5)
	v_mfma_f32_16x16x32_bf16 v[54:57], v[166:169], v[154:157], v[54:57]
	s_waitcnt lgkmcnt(4)
	v_mfma_f32_16x16x32_bf16 v[58:61], v[170:173], v[150:153], v[58:61]
	v_mfma_f32_16x16x32_bf16 v[62:65], v[170:173], v[154:157], v[62:65]
	ds_read_b128 v[214:217], v148 offset:55376
	ds_read_b128 v[198:201], v147 offset:18512
	ds_read_b128 v[202:205], v147 offset:20816
	ds_read_b128 v[218:221], v148 offset:57680
	s_waitcnt lgkmcnt(7)
	v_mfma_f32_16x16x32_bf16 v[18:21], v[166:169], v[158:161], v[18:21]
	v_mfma_f32_16x16x32_bf16 v[26:29], v[170:173], v[158:161], v[26:29]
	s_waitcnt lgkmcnt(6)
	v_mfma_f32_16x16x32_bf16 v[22:25], v[166:169], v[162:165], v[22:25]
	v_mfma_f32_16x16x32_bf16 v[30:33], v[170:173], v[162:165], v[30:33]
	ds_read_b128 v[206:209], v147 offset:23120
	ds_read_b128 v[210:213], v147 offset:25424
	ds_read_b128 v[222:225], v148 offset:59984
	ds_read_b128 v[226:229], v148 offset:62288
	s_waitcnt lgkmcnt(9)
	v_mfma_f32_16x16x32_bf16 v[34:37], v[174:177], v[150:153], v[34:37]
	v_mfma_f32_16x16x32_bf16 v[38:41], v[174:177], v[154:157], v[38:41]
	v_mfma_f32_16x16x32_bf16 v[2:5], v[174:177], v[158:161], v[2:5]
	v_mfma_f32_16x16x32_bf16 v[6:9], v[174:177], v[162:165], v[6:9]
	s_waitcnt lgkmcnt(8)
	v_mfma_f32_16x16x32_bf16 v[42:45], v[178:181], v[150:153], v[42:45]
	v_mfma_f32_16x16x32_bf16 v[46:49], v[178:181], v[154:157], v[46:49]
	v_mfma_f32_16x16x32_bf16 v[10:13], v[178:181], v[158:161], v[10:13]
	v_mfma_f32_16x16x32_bf16 v[14:17], v[178:181], v[162:165], v[14:17]
	s_waitcnt lgkmcnt(6)
	v_mfma_f32_16x16x32_bf16 v[50:53], v[214:217], v[198:201], v[50:53]
	s_waitcnt lgkmcnt(5)
	v_mfma_f32_16x16x32_bf16 v[54:57], v[214:217], v[202:205], v[54:57]
	s_waitcnt lgkmcnt(4)
	v_mfma_f32_16x16x32_bf16 v[58:61], v[218:221], v[198:201], v[58:61]
	v_mfma_f32_16x16x32_bf16 v[62:65], v[218:221], v[202:205], v[62:65]
	s_waitcnt lgkmcnt(3)
	v_mfma_f32_16x16x32_bf16 v[18:21], v[214:217], v[206:209], v[18:21]
	v_mfma_f32_16x16x32_bf16 v[26:29], v[218:221], v[206:209], v[26:29]
	s_waitcnt lgkmcnt(2)
	v_mfma_f32_16x16x32_bf16 v[22:25], v[214:217], v[210:213], v[22:25]
	v_mfma_f32_16x16x32_bf16 v[30:33], v[218:221], v[210:213], v[30:33]
	s_waitcnt lgkmcnt(1)
	v_mfma_f32_16x16x32_bf16 v[34:37], v[222:225], v[198:201], v[34:37]
	v_mfma_f32_16x16x32_bf16 v[38:41], v[222:225], v[202:205], v[38:41]
	v_mfma_f32_16x16x32_bf16 v[2:5], v[222:225], v[206:209], v[2:5]
	v_mfma_f32_16x16x32_bf16 v[6:9], v[222:225], v[210:213], v[6:9]
	s_waitcnt lgkmcnt(0)
	v_mfma_f32_16x16x32_bf16 v[42:45], v[226:229], v[198:201], v[42:45]
	v_mfma_f32_16x16x32_bf16 v[46:49], v[226:229], v[202:205], v[46:49]
	v_mfma_f32_16x16x32_bf16 v[10:13], v[226:229], v[206:209], v[10:13]
	v_mfma_f32_16x16x32_bf16 v[14:17], v[226:229], v[210:213], v[14:17]
	s_nop 7
	s_nop 7
	v_permlane16_swap_b32_e32 v50, v54
	v_permlane16_swap_b32_e32 v51, v55
	v_permlane16_swap_b32_e32 v52, v56
	v_permlane16_swap_b32_e32 v53, v57
	v_permlane16_swap_b32_e32 v58, v62
	v_permlane16_swap_b32_e32 v59, v63
	v_permlane16_swap_b32_e32 v60, v64
	v_permlane16_swap_b32_e32 v61, v65
	v_permlane16_swap_b32_e32 v34, v38
	v_permlane16_swap_b32_e32 v35, v39
	v_permlane16_swap_b32_e32 v36, v40
	v_permlane16_swap_b32_e32 v37, v41
	v_permlane16_swap_b32_e32 v42, v46
	v_permlane16_swap_b32_e32 v43, v47
	v_permlane16_swap_b32_e32 v44, v48
	v_permlane16_swap_b32_e32 v45, v49
	v_permlane16_swap_b32_e32 v18, v22
	v_permlane16_swap_b32_e32 v19, v23
	v_permlane16_swap_b32_e32 v20, v24
	v_permlane16_swap_b32_e32 v21, v25
	v_permlane16_swap_b32_e32 v26, v30
	v_permlane16_swap_b32_e32 v27, v31
	v_permlane16_swap_b32_e32 v28, v32
	v_permlane16_swap_b32_e32 v29, v33
	v_permlane16_swap_b32_e32 v2, v6
	v_permlane16_swap_b32_e32 v3, v7
	v_permlane16_swap_b32_e32 v4, v8
	v_permlane16_swap_b32_e32 v5, v9
	v_permlane16_swap_b32_e32 v10, v14
	v_permlane16_swap_b32_e32 v11, v15
	v_permlane16_swap_b32_e32 v12, v16
	v_permlane16_swap_b32_e32 v13, v17
	v_permlane32_swap_b32_e32 v50, v54
	v_permlane32_swap_b32_e32 v51, v55
	v_permlane32_swap_b32_e32 v52, v56
	v_permlane32_swap_b32_e32 v53, v57
	v_permlane32_swap_b32_e32 v58, v62
	v_permlane32_swap_b32_e32 v59, v63
	v_permlane32_swap_b32_e32 v60, v64
	v_permlane32_swap_b32_e32 v61, v65
	v_permlane32_swap_b32_e32 v34, v38
	v_permlane32_swap_b32_e32 v35, v39
	v_permlane32_swap_b32_e32 v36, v40
	v_permlane32_swap_b32_e32 v37, v41
	v_permlane32_swap_b32_e32 v42, v46
	v_permlane32_swap_b32_e32 v43, v47
	v_permlane32_swap_b32_e32 v44, v48
	v_permlane32_swap_b32_e32 v45, v49
	v_permlane32_swap_b32_e32 v18, v22
	v_permlane32_swap_b32_e32 v19, v23
	v_permlane32_swap_b32_e32 v20, v24
	v_permlane32_swap_b32_e32 v21, v25
	v_permlane32_swap_b32_e32 v26, v30
	v_permlane32_swap_b32_e32 v27, v31
	v_permlane32_swap_b32_e32 v28, v32
	v_permlane32_swap_b32_e32 v29, v33
	v_permlane32_swap_b32_e32 v2, v6
	v_permlane32_swap_b32_e32 v3, v7
	v_permlane32_swap_b32_e32 v4, v8
	v_permlane32_swap_b32_e32 v5, v9
	v_permlane32_swap_b32_e32 v10, v14
	v_permlane32_swap_b32_e32 v11, v15
	v_permlane32_swap_b32_e32 v12, v16
	v_permlane32_swap_b32_e32 v13, v17
	s_waitcnt lgkmcnt(0)
	s_barrier
	s_branch .LBB0_952
